# latent Hyena items store z = scale*acc + bias*u transposed (f32, contiguous) instead of walking a column of x1/ymix with 2-byte accesses; x1 multiply + bf16 rounding moved to a tiled LDS-transpose pas
# speedup vs baseline: 1.0615x; 1.0615x over previous
; DI u32 pack2(float a, float b) { return (u32)f2bf(a) | ((u32)f2bf(b) << 16); }
; DI float bflo(u32 v) { return __uint_as_float(v << 16); }
; DI float bfhi(u32 v) { return __uint_as_float(v & 0xffff0000u); }
; DI void ssd_item(const Params& p, int l, int it, char* smem) {
;     ...
;     for (int ks = 4; ks < 8; ++ks) creg[ks] = *(const bf16x8*)(cr + ks * 16);
;     f32x16 acc[4], yd[2];
; #pragma unroll
;     for (int i = 0; i < 4; ++i)
; #pragma unroll
;       for (int r = 0; r < 16; ++r) acc[i][r] = 0.f;
; #pragma unroll
;     for (int i = 0; i < 2; ++i)
; #pragma unroll
;       for (int r = 0; r < 16; ++r) yd[i][r] = 0.f;
; #pragma unroll
;     for (int ks = 0; ks < 8; ++ks) {
;       const bf16x8 areg = creg[ks];
; #pragma unroll
;       for (int jb = 0; jb < 4; ++jb) {
;         const bf16x8 bb = *(const bf16x8*)&BG[(jb * 32 + l32) * 136 + ks * 16 + h * 8];
;         acc[jb] = __builtin_amdgcn_mfma_f32_32x32x16_bf16(areg, bb, acc[jb], 0, 0, 0);
;       }
;     }
;     {
;       const float eai = fea[w * 32 + l32];
; #pragma unroll
;       for (int ks = 0; ks < 8; ++ks) {
;         union { u32 u[4]; bf16x8 v; } t;
;         t.v = creg[ks];
; #pragma unroll
;         for (int q = 0; q < 4; ++q) t.u[q] = pack2(bflo(t.u[q]) * eai, bfhi(t.u[q]) * eai);
; #pragma unroll
;         for (int pb = 0; pb < 2; ++pb) {
;           const bf16x8 bb = *(const bf16x8*)&HL[(pb * 32 + l32) * 136 + ks * 16 + h * 8];
;           yd[pb] = __builtin_amdgcn_mfma_f32_32x32x16_bf16(t.v, bb, yd[pb], 0, 0, 0);
;         }
;       }
;     }
.LBB0_996:
	s_or_b64 exec, exec, s[0:1]
	s_waitcnt lgkmcnt(0)
	s_barrier
	global_load_dwordx4 v[152:155], v[36:37], off offset:1664
	global_load_dwordx4 v[148:151], v[36:37], off offset:1696
	global_load_dwordx4 v[144:147], v[36:37], off offset:1728
	global_load_dwordx4 v[140:143], v[36:37], off offset:1760
	ds_read_b128 v[36:39], v197
	ds_read_b128 v[40:43], v197 offset:32
	s_waitcnt lgkmcnt(1)
	v_mfma_f32_32x32x16_bf16 v[112:127], v[32:35], v[36:39], 0
	ds_read_b128 v[36:39], v197 offset:8704
	v_lshlrev_b32_e32 v241, 16, v137
	v_lshlrev_b32_e32 v240, 16, v136
	v_lshlrev_b32_e32 v243, 16, v139
	v_lshlrev_b32_e32 v242, 16, v138
	ds_read_b32 v156, v239 offset:53760
	s_waitcnt lgkmcnt(0)
	v_pk_mul_f32 v[240:241], v[156:157], v[240:241] op_sel_hi:[0,1]
	v_mfma_f32_32x32x16_bf16 v[96:111], v[32:35], v[36:39], 0
	ds_read_b128 v[36:39], v197 offset:17408
	v_mul_f32_e64 v242, v156, v242
	v_mul_f32_e64 v243, v156, v243
	s_waitcnt lgkmcnt(0)
	v_mfma_f32_32x32x16_bf16 v[80:95], v[32:35], v[36:39], 0
	ds_read_b128 v[36:39], v197 offset:26112
	s_waitcnt lgkmcnt(0)
	v_mfma_f32_32x32x16_bf16 v[64:79], v[32:35], v[36:39], 0
	ds_read_b128 v[36:39], v197 offset:8736
	s_waitcnt lgkmcnt(0)
	v_mfma_f32_32x32x16_bf16 v[96:111], v[136:139], v[36:39], v[96:111]
	ds_read_b128 v[36:39], v197 offset:17440
	s_waitcnt lgkmcnt(0)
	v_mfma_f32_32x32x16_bf16 v[80:95], v[136:139], v[36:39], v[80:95]
	ds_read_b128 v[36:39], v197 offset:26144
	v_mfma_f32_32x32x16_bf16 v[112:127], v[136:139], v[40:43], v[112:127]
	s_waitcnt lgkmcnt(0)
	v_mfma_f32_32x32x16_bf16 v[64:79], v[136:139], v[36:39], v[64:79]
	ds_read_b128 v[36:39], v197 offset:64
	v_and_b32_e32 v137, 0xffff0000, v137
	v_and_b32_e32 v136, 0xffff0000, v136
	v_and_b32_e32 v139, 0xffff0000, v139
	v_and_b32_e32 v138, 0xffff0000, v138
	v_pk_mul_f32 v[136:137], v[156:157], v[136:137] op_sel_hi:[0,1]
	v_pk_mul_f32 v[138:139], v[156:157], v[138:139] op_sel_hi:[0,1]
	s_waitcnt lgkmcnt(0)
	v_mfma_f32_32x32x16_bf16 v[112:127], v[132:135], v[36:39], v[112:127]
	ds_read_b128 v[36:39], v197 offset:8768
	v_bfe_u32 v175, v139, 16, 1
	v_bfe_u32 v199, v138, 16, 1
	v_bfe_u32 v206, v137, 16, 1
	v_bfe_u32 v207, v136, 16, 1
	v_add3_u32 v136, v136, v207, s76
	v_add3_u32 v137, v137, v206, s76
	s_waitcnt lgkmcnt(0)
	v_mfma_f32_32x32x16_bf16 v[96:111], v[132:135], v[36:39], v[96:111]
	ds_read_b128 v[36:39], v197 offset:17472
	v_add3_u32 v138, v138, v199, s76
	v_add3_u32 v139, v139, v175, s76
	v_bfe_u32 v175, v240, 16, 1
	v_bfe_u32 v199, v241, 16, 1
	v_bfe_u32 v206, v242, 16, 1
	v_bfe_u32 v207, v243, 16, 1
	s_waitcnt lgkmcnt(0)
	v_mfma_f32_32x32x16_bf16 v[80:95], v[132:135], v[36:39], v[80:95]
	ds_read_b128 v[36:39], v197 offset:26176
	v_add3_u32 v207, v243, v207, s76
	v_add3_u32 v206, v242, v206, s76
	v_add3_u32 v199, v241, v199, s76
	v_add3_u32 v175, v240, v175, s76
	v_lshrrev_b32_e32 v175, 16, v175
	v_lshrrev_b32_e32 v199, 16, v199
	s_waitcnt lgkmcnt(0)
	v_mfma_f32_32x32x16_bf16 v[64:79], v[132:135], v[36:39], v[64:79]
	ds_read_b128 v[36:39], v197 offset:96
	v_lshrrev_b32_e32 v206, 16, v206
	v_lshrrev_b32_e32 v207, 16, v207
	v_and_or_b32 v139, v139, s77, v207
	v_and_or_b32 v138, v138, s77, v206
	v_and_or_b32 v137, v137, s77, v199
	v_and_or_b32 v136, v136, s77, v175
	s_waitcnt lgkmcnt(0)
	v_mfma_f32_32x32x16_bf16 v[112:127], v[128:131], v[36:39], v[112:127]
	ds_read_b128 v[36:39], v197 offset:8800
	ds_read_b128 v[240:243], v197 offset:34848
	s_waitcnt lgkmcnt(1)
	v_mfma_f32_32x32x16_bf16 v[96:111], v[128:131], v[36:39], v[96:111]
	ds_read_b128 v[36:39], v197 offset:17504
	s_waitcnt lgkmcnt(0)
	v_mfma_f32_32x32x16_bf16 v[80:95], v[128:131], v[36:39], v[80:95]
	ds_read_b128 v[36:39], v197 offset:26208
	s_waitcnt lgkmcnt(0)
	v_mfma_f32_32x32x16_bf16 v[64:79], v[128:131], v[36:39], v[64:79]
	ds_read_b128 v[36:39], v197 offset:128
	s_waitcnt vmcnt(3) lgkmcnt(0)
	v_mfma_f32_32x32x16_bf16 v[112:127], v[152:155], v[36:39], v[112:127]
	ds_read_b128 v[36:39], v197 offset:8832
	s_waitcnt lgkmcnt(0)
	v_mfma_f32_32x32x16_bf16 v[96:111], v[152:155], v[36:39], v[96:111]
	ds_read_b128 v[36:39], v197 offset:17536
	s_waitcnt lgkmcnt(0)
	v_mfma_f32_32x32x16_bf16 v[80:95], v[152:155], v[36:39], v[80:95]
	ds_read_b128 v[36:39], v197 offset:26240
	s_waitcnt lgkmcnt(0)
	v_mfma_f32_32x32x16_bf16 v[64:79], v[152:155], v[36:39], v[64:79]
	ds_read_b128 v[36:39], v197 offset:160
	s_waitcnt vmcnt(2) lgkmcnt(0)
	v_mfma_f32_32x32x16_bf16 v[112:127], v[148:151], v[36:39], v[112:127]
	ds_read_b128 v[36:39], v197 offset:8864
	s_waitcnt lgkmcnt(0)
	v_mfma_f32_32x32x16_bf16 v[96:111], v[148:151], v[36:39], v[96:111]
	ds_read_b128 v[36:39], v197 offset:17568
	s_waitcnt lgkmcnt(0)
	v_mfma_f32_32x32x16_bf16 v[80:95], v[148:151], v[36:39], v[80:95]
	ds_read_b128 v[36:39], v197 offset:26272
	s_waitcnt lgkmcnt(0)
	v_mfma_f32_32x32x16_bf16 v[64:79], v[148:151], v[36:39], v[64:79]
	ds_read_b128 v[36:39], v197 offset:192
	s_waitcnt vmcnt(1) lgkmcnt(0)
	v_mfma_f32_32x32x16_bf16 v[112:127], v[144:147], v[36:39], v[112:127]
	ds_read_b128 v[36:39], v197 offset:8896
	s_waitcnt lgkmcnt(0)
	v_mfma_f32_32x32x16_bf16 v[96:111], v[144:147], v[36:39], v[96:111]
	ds_read_b128 v[36:39], v197 offset:17600
	s_waitcnt lgkmcnt(0)
	v_mfma_f32_32x32x16_bf16 v[80:95], v[144:147], v[36:39], v[80:95]
	ds_read_b128 v[36:39], v197 offset:26304
	s_waitcnt lgkmcnt(0)
	v_mfma_f32_32x32x16_bf16 v[64:79], v[144:147], v[36:39], v[64:79]
	ds_read_b128 v[36:39], v197 offset:224
	s_waitcnt vmcnt(0) lgkmcnt(0)
	v_mfma_f32_32x32x16_bf16 v[112:127], v[140:143], v[36:39], v[112:127]
	ds_read_b128 v[36:39], v197 offset:8928
	s_waitcnt lgkmcnt(0)
	v_mfma_f32_32x32x16_bf16 v[96:111], v[140:143], v[36:39], v[96:111]
	ds_read_b128 v[36:39], v197 offset:17632
	s_waitcnt lgkmcnt(0)
; DI u32 pack2(float a, float b) { return (u32)f2bf(a) | ((u32)f2bf(b) << 16); }
; DI float bflo(u32 v) { return __uint_as_float(v << 16); }
; DI float bfhi(u32 v) { return __uint_as_float(v & 0xffff0000u); }
; DI void ssd_item(const Params& p, int l, int it, char* smem) {
;     ...
;     {
;       const float eai = fea[w * 32 + l32];
; #pragma unroll
;       for (int ks = 0; ks < 8; ++ks) {
;         union { u32 u[4]; bf16x8 v; } t;
;         t.v = creg[ks];
; #pragma unroll
;         for (int q = 0; q < 4; ++q) t.u[q] = pack2(bflo(t.u[q]) * eai, bfhi(t.u[q]) * eai);
; #pragma unroll
;         for (int pb = 0; pb < 2; ++pb) {
;           const bf16x8 bb = *(const bf16x8*)&HL[(pb * 32 + l32) * 136 + ks * 16 + h * 8];
;           yd[pb] = __builtin_amdgcn_mfma_f32_32x32x16_bf16(t.v, bb, yd[pb], 0, 0, 0);
;         }
;       }
;     }
	v_mfma_f32_32x32x16_bf16 v[80:95], v[140:143], v[36:39], v[80:95]
	ds_read_b128 v[36:39], v197 offset:26336
	s_waitcnt lgkmcnt(0)
	v_mfma_f32_32x32x16_bf16 v[64:79], v[140:143], v[36:39], v[64:79]
	v_lshlrev_b32_e32 v37, 16, v33
	v_lshlrev_b32_e32 v36, 16, v32
	v_and_b32_e32 v33, 0xffff0000, v33
	v_and_b32_e32 v32, 0xffff0000, v32
	v_lshlrev_b32_e32 v39, 16, v35
	v_lshlrev_b32_e32 v38, 16, v34
	v_and_b32_e32 v35, 0xffff0000, v35
	v_and_b32_e32 v34, 0xffff0000, v34
	v_pk_mul_f32 v[32:33], v[156:157], v[32:33] op_sel_hi:[0,1]
	v_pk_mul_f32 v[34:35], v[156:157], v[34:35] op_sel_hi:[0,1]
	v_pk_mul_f32 v[36:37], v[156:157], v[36:37] op_sel_hi:[0,1]
	v_pk_mul_f32 v[38:39], v[156:157], v[38:39] op_sel_hi:[0,1]
	v_bfe_u32 v40, v35, 16, 1
	v_bfe_u32 v41, v34, 16, 1
	v_bfe_u32 v42, v33, 16, 1
	v_bfe_u32 v43, v32, 16, 1
	v_add3_u32 v32, v32, v43, s76
	v_add3_u32 v33, v33, v42, s76
	v_add3_u32 v34, v34, v41, s76
	v_add3_u32 v35, v35, v40, s76
	v_bfe_u32 v40, v36, 16, 1
	v_bfe_u32 v41, v37, 16, 1
	v_bfe_u32 v42, v38, 16, 1
	v_bfe_u32 v43, v39, 16, 1
	v_add3_u32 v39, v39, v43, s76
	v_add3_u32 v38, v38, v42, s76
	v_add3_u32 v37, v37, v41, s76
	v_add3_u32 v36, v36, v40, s76
	v_lshrrev_b32_e32 v36, 16, v36
	v_lshrrev_b32_e32 v37, 16, v37
	v_lshrrev_b32_e32 v38, 16, v38
	v_lshrrev_b32_e32 v39, 16, v39
	v_and_or_b32 v35, v35, s77, v39
	v_and_or_b32 v34, v34, s77, v38
	v_and_or_b32 v33, v33, s77, v37
	v_and_or_b32 v32, v32, s77, v36
	ds_read_b128 v[36:39], v197 offset:34816
	s_waitcnt lgkmcnt(0)
	v_mfma_f32_32x32x16_bf16 v[48:63], v[32:35], v[36:39], 0
	ds_read_b128 v[36:39], v197 offset:43520
	v_mfma_f32_32x32x16_bf16 v[48:63], v[136:139], v[240:243], v[48:63]
	ds_read_b128 v[240:243], v197 offset:43552
	s_waitcnt lgkmcnt(1)
	v_mfma_f32_32x32x16_bf16 v[32:47], v[32:35], v[36:39], 0
	s_waitcnt lgkmcnt(0)
	v_mfma_f32_32x32x16_bf16 v[32:47], v[136:139], v[240:243], v[32:47]
	v_lshlrev_b32_e32 v137, 16, v133
	v_lshlrev_b32_e32 v136, 16, v132
	v_and_b32_e32 v133, 0xffff0000, v133
	v_and_b32_e32 v132, 0xffff0000, v132
	v_lshlrev_b32_e32 v139, 16, v135
	v_lshlrev_b32_e32 v138, 16, v134
	v_and_b32_e32 v135, 0xffff0000, v135
	v_and_b32_e32 v134, 0xffff0000, v134
	v_pk_mul_f32 v[132:133], v[156:157], v[132:133] op_sel_hi:[0,1]
	v_pk_mul_f32 v[134:135], v[156:157], v[134:135] op_sel_hi:[0,1]
	v_pk_mul_f32 v[136:137], v[156:157], v[136:137] op_sel_hi:[0,1]
	v_pk_mul_f32 v[138:139], v[156:157], v[138:139] op_sel_hi:[0,1]
	v_bfe_u32 v175, v135, 16, 1
	v_bfe_u32 v199, v134, 16, 1
	v_bfe_u32 v206, v133, 16, 1
	v_bfe_u32 v207, v132, 16, 1
	v_add3_u32 v132, v132, v207, s76
	v_add3_u32 v133, v133, v206, s76
	v_add3_u32 v134, v134, v199, s76
	v_add3_u32 v135, v135, v175, s76
	v_bfe_u32 v175, v136, 16, 1
	v_bfe_u32 v199, v137, 16, 1
	v_bfe_u32 v206, v138, 16, 1
	v_bfe_u32 v207, v139, 16, 1
	v_add3_u32 v139, v139, v207, s76
	v_add3_u32 v138, v138, v206, s76
	v_add3_u32 v137, v137, v199, s76
	v_add3_u32 v136, v136, v175, s76
	v_lshrrev_b32_e32 v136, 16, v136
	v_lshrrev_b32_e32 v137, 16, v137
	v_lshrrev_b32_e32 v138, 16, v138
	v_lshrrev_b32_e32 v139, 16, v139
	v_and_or_b32 v135, v135, s77, v139
	v_and_or_b32 v134, v134, s77, v138
	v_and_or_b32 v133, v133, s77, v137
	v_and_or_b32 v132, v132, s77, v136
	ds_read_b128 v[136:139], v197 offset:34880
	s_waitcnt lgkmcnt(0)
	v_mfma_f32_32x32x16_bf16 v[48:63], v[132:135], v[136:139], v[48:63]
	ds_read_b128 v[136:139], v197 offset:43584
	s_waitcnt lgkmcnt(0)
	v_mfma_f32_32x32x16_bf16 v[32:47], v[132:135], v[136:139], v[32:47]
	v_lshlrev_b32_e32 v133, 16, v129
	v_lshlrev_b32_e32 v132, 16, v128
	v_and_b32_e32 v129, 0xffff0000, v129
	v_and_b32_e32 v128, 0xffff0000, v128
	v_lshlrev_b32_e32 v135, 16, v131
	v_lshlrev_b32_e32 v134, 16, v130
	v_and_b32_e32 v131, 0xffff0000, v131
	v_and_b32_e32 v130, 0xffff0000, v130
	v_pk_mul_f32 v[128:129], v[156:157], v[128:129] op_sel_hi:[0,1]
	v_pk_mul_f32 v[130:131], v[156:157], v[130:131] op_sel_hi:[0,1]
	v_pk_mul_f32 v[132:133], v[156:157], v[132:133] op_sel_hi:[0,1]
	v_pk_mul_f32 v[134:135], v[156:157], v[134:135] op_sel_hi:[0,1]
	v_bfe_u32 v136, v131, 16, 1
	v_bfe_u32 v137, v130, 16, 1
	v_bfe_u32 v138, v129, 16, 1
	v_bfe_u32 v139, v128, 16, 1
	v_add3_u32 v128, v128, v139, s76
	v_add3_u32 v129, v129, v138, s76
	v_add3_u32 v130, v130, v137, s76
	v_add3_u32 v131, v131, v136, s76
	v_bfe_u32 v136, v132, 16, 1
	v_bfe_u32 v137, v133, 16, 1
	v_bfe_u32 v138, v134, 16, 1
	v_bfe_u32 v139, v135, 16, 1
	v_add3_u32 v135, v135, v139, s76
	v_add3_u32 v134, v134, v138, s76
	v_add3_u32 v133, v133, v137, s76
	v_add3_u32 v132, v132, v136, s76
	v_lshrrev_b32_e32 v132, 16, v132
	v_lshrrev_b32_e32 v133, 16, v133
	v_lshrrev_b32_e32 v134, 16, v134
	v_lshrrev_b32_e32 v135, 16, v135
	v_and_or_b32 v131, v131, s77, v135
	v_and_or_b32 v130, v130, s77, v134
	v_and_or_b32 v129, v129, s77, v133
	v_and_or_b32 v128, v128, s77, v132
	ds_read_b128 v[132:135], v197 offset:34912
	s_waitcnt lgkmcnt(0)
	v_mfma_f32_32x32x16_bf16 v[48:63], v[128:131], v[132:135], v[48:63]
	ds_read_b128 v[132:135], v197 offset:43616
	s_waitcnt lgkmcnt(0)
; DI u32 pack2(float a, float b) { return (u32)f2bf(a) | ((u32)f2bf(b) << 16); }
; DI float bflo(u32 v) { return __uint_as_float(v << 16); }
; DI float bfhi(u32 v) { return __uint_as_float(v & 0xffff0000u); }
; DI void ssd_item(const Params& p, int l, int it, char* smem) {
;     ...
;     {
;       const float eai = fea[w * 32 + l32];
; #pragma unroll
;       for (int ks = 0; ks < 8; ++ks) {
;         union { u32 u[4]; bf16x8 v; } t;
;         t.v = creg[ks];
; #pragma unroll
;         for (int q = 0; q < 4; ++q) t.u[q] = pack2(bflo(t.u[q]) * eai, bfhi(t.u[q]) * eai);
; #pragma unroll
;         for (int pb = 0; pb < 2; ++pb) {
;           const bf16x8 bb = *(const bf16x8*)&HL[(pb * 32 + l32) * 136 + ks * 16 + h * 8];
;           yd[pb] = __builtin_amdgcn_mfma_f32_32x32x16_bf16(t.v, bb, yd[pb], 0, 0, 0);
;         }
;       }
;     }
;     __syncthreads();
	v_mfma_f32_32x32x16_bf16 v[32:47], v[128:131], v[132:135], v[32:47]
	v_and_b32_e32 v131, 0xffff0000, v153
	v_and_b32_e32 v130, 0xffff0000, v152
	v_and_b32_e32 v135, 0xffff0000, v155
	v_and_b32_e32 v134, 0xffff0000, v154
	v_lshlrev_b32_e32 v129, 16, v153
	v_lshlrev_b32_e32 v128, 16, v152
	v_pk_mul_f32 v[130:131], v[156:157], v[130:131] op_sel_hi:[0,1]
	v_lshlrev_b32_e32 v133, 16, v155
	v_lshlrev_b32_e32 v132, 16, v154
	v_pk_mul_f32 v[134:135], v[156:157], v[134:135] op_sel_hi:[0,1]
	v_pk_mul_f32 v[128:129], v[156:157], v[128:129] op_sel_hi:[0,1]
	v_pk_mul_f32 v[132:133], v[156:157], v[132:133] op_sel_hi:[0,1]
	v_bfe_u32 v136, v135, 16, 1
	v_bfe_u32 v137, v134, 16, 1
	v_bfe_u32 v138, v131, 16, 1
	v_bfe_u32 v139, v130, 16, 1
	v_add3_u32 v139, v130, v139, s76
	v_add3_u32 v138, v131, v138, s76
	v_add3_u32 v130, v134, v137, s76
	v_add3_u32 v131, v135, v136, s76
	v_bfe_u32 v134, v128, 16, 1
	v_bfe_u32 v135, v129, 16, 1
	v_bfe_u32 v136, v132, 16, 1
	v_bfe_u32 v137, v133, 16, 1
	v_add3_u32 v133, v133, v137, s76
	v_add3_u32 v132, v132, v136, s76
	v_add3_u32 v129, v129, v135, s76
	v_add3_u32 v128, v128, v134, s76
	v_lshrrev_b32_e32 v128, 16, v128
	v_lshrrev_b32_e32 v129, 16, v129
	v_lshrrev_b32_e32 v132, 16, v132
	v_lshrrev_b32_e32 v133, 16, v133
	v_and_or_b32 v131, v131, s77, v133
	v_and_or_b32 v130, v130, s77, v132
	v_and_or_b32 v129, v138, s77, v129
	v_and_or_b32 v128, v139, s77, v128
	ds_read_b128 v[132:135], v197 offset:34944
	s_waitcnt lgkmcnt(0)
	v_mfma_f32_32x32x16_bf16 v[48:63], v[128:131], v[132:135], v[48:63]
	ds_read_b128 v[132:135], v197 offset:43648
	s_waitcnt lgkmcnt(0)
	v_mfma_f32_32x32x16_bf16 v[32:47], v[128:131], v[132:135], v[32:47]
	v_and_b32_e32 v131, 0xffff0000, v149
	v_and_b32_e32 v130, 0xffff0000, v148
	v_and_b32_e32 v135, 0xffff0000, v151
	v_and_b32_e32 v134, 0xffff0000, v150
	v_lshlrev_b32_e32 v129, 16, v149
	v_lshlrev_b32_e32 v128, 16, v148
	v_pk_mul_f32 v[130:131], v[156:157], v[130:131] op_sel_hi:[0,1]
	v_lshlrev_b32_e32 v133, 16, v151
	v_lshlrev_b32_e32 v132, 16, v150
	v_pk_mul_f32 v[134:135], v[156:157], v[134:135] op_sel_hi:[0,1]
	v_pk_mul_f32 v[128:129], v[156:157], v[128:129] op_sel_hi:[0,1]
	v_pk_mul_f32 v[132:133], v[156:157], v[132:133] op_sel_hi:[0,1]
	v_bfe_u32 v136, v135, 16, 1
	v_bfe_u32 v137, v134, 16, 1
	v_bfe_u32 v138, v131, 16, 1
	v_bfe_u32 v139, v130, 16, 1
	v_add3_u32 v139, v130, v139, s76
	v_add3_u32 v138, v131, v138, s76
	v_add3_u32 v130, v134, v137, s76
	v_add3_u32 v131, v135, v136, s76
	v_bfe_u32 v134, v128, 16, 1
	v_bfe_u32 v135, v129, 16, 1
	v_bfe_u32 v136, v132, 16, 1
	v_bfe_u32 v137, v133, 16, 1
	v_add3_u32 v133, v133, v137, s76
	v_add3_u32 v132, v132, v136, s76
	v_add3_u32 v129, v129, v135, s76
	v_add3_u32 v128, v128, v134, s76
	v_lshrrev_b32_e32 v128, 16, v128
	v_lshrrev_b32_e32 v129, 16, v129
	v_lshrrev_b32_e32 v132, 16, v132
	v_lshrrev_b32_e32 v133, 16, v133
	v_and_or_b32 v131, v131, s77, v133
	v_and_or_b32 v130, v130, s77, v132
	v_and_or_b32 v129, v138, s77, v129
	v_and_or_b32 v128, v139, s77, v128
	ds_read_b128 v[132:135], v197 offset:34976
	s_waitcnt lgkmcnt(0)
	v_mfma_f32_32x32x16_bf16 v[48:63], v[128:131], v[132:135], v[48:63]
	ds_read_b128 v[132:135], v197 offset:43680
	s_waitcnt lgkmcnt(0)
	v_mfma_f32_32x32x16_bf16 v[32:47], v[128:131], v[132:135], v[32:47]
	v_and_b32_e32 v131, 0xffff0000, v145
	v_and_b32_e32 v130, 0xffff0000, v144
	v_and_b32_e32 v135, 0xffff0000, v147
	v_and_b32_e32 v134, 0xffff0000, v146
	v_lshlrev_b32_e32 v129, 16, v145
	v_lshlrev_b32_e32 v128, 16, v144
	v_pk_mul_f32 v[130:131], v[156:157], v[130:131] op_sel_hi:[0,1]
	v_lshlrev_b32_e32 v133, 16, v147
	v_lshlrev_b32_e32 v132, 16, v146
	v_pk_mul_f32 v[134:135], v[156:157], v[134:135] op_sel_hi:[0,1]
	v_pk_mul_f32 v[128:129], v[156:157], v[128:129] op_sel_hi:[0,1]
	v_pk_mul_f32 v[132:133], v[156:157], v[132:133] op_sel_hi:[0,1]
	v_bfe_u32 v136, v135, 16, 1
	v_bfe_u32 v137, v134, 16, 1
	v_bfe_u32 v138, v131, 16, 1
	v_bfe_u32 v139, v130, 16, 1
	v_add3_u32 v139, v130, v139, s76
	v_add3_u32 v138, v131, v138, s76
	v_add3_u32 v130, v134, v137, s76
	v_add3_u32 v131, v135, v136, s76
	v_bfe_u32 v134, v128, 16, 1
	v_bfe_u32 v135, v129, 16, 1
	v_bfe_u32 v136, v132, 16, 1
	v_bfe_u32 v137, v133, 16, 1
	v_add3_u32 v133, v133, v137, s76
	v_add3_u32 v132, v132, v136, s76
	v_add3_u32 v129, v129, v135, s76
	v_add3_u32 v128, v128, v134, s76
	v_lshrrev_b32_e32 v128, 16, v128
	v_lshrrev_b32_e32 v129, 16, v129
	v_lshrrev_b32_e32 v132, 16, v132
	v_lshrrev_b32_e32 v133, 16, v133
	v_and_or_b32 v131, v131, s77, v133
	v_and_or_b32 v130, v130, s77, v132
	v_and_or_b32 v129, v138, s77, v129
	v_and_or_b32 v128, v139, s77, v128
	ds_read_b128 v[132:135], v197 offset:35008
	s_waitcnt lgkmcnt(0)
	v_mfma_f32_32x32x16_bf16 v[48:63], v[128:131], v[132:135], v[48:63]
	ds_read_b128 v[132:135], v197 offset:43712
	s_waitcnt lgkmcnt(0)
	v_mfma_f32_32x32x16_bf16 v[32:47], v[128:131], v[132:135], v[32:47]
	v_and_b32_e32 v131, 0xffff0000, v141
	v_and_b32_e32 v130, 0xffff0000, v140
	v_and_b32_e32 v135, 0xffff0000, v143
	v_and_b32_e32 v134, 0xffff0000, v142
	v_lshlrev_b32_e32 v129, 16, v141
	v_lshlrev_b32_e32 v128, 16, v140
	v_pk_mul_f32 v[130:131], v[156:157], v[130:131] op_sel_hi:[0,1]
	v_lshlrev_b32_e32 v133, 16, v143
	v_lshlrev_b32_e32 v132, 16, v142
	v_pk_mul_f32 v[134:135], v[156:157], v[134:135] op_sel_hi:[0,1]
	v_pk_mul_f32 v[128:129], v[156:157], v[128:129] op_sel_hi:[0,1]
	v_pk_mul_f32 v[132:133], v[156:157], v[132:133] op_sel_hi:[0,1]
	v_bfe_u32 v136, v135, 16, 1
	v_bfe_u32 v137, v134, 16, 1
	v_bfe_u32 v138, v131, 16, 1
	v_bfe_u32 v139, v130, 16, 1
	v_add3_u32 v139, v130, v139, s76
	v_add3_u32 v138, v131, v138, s76
	v_add3_u32 v130, v134, v137, s76
	v_add3_u32 v131, v135, v136, s76
	v_bfe_u32 v134, v128, 16, 1
	v_bfe_u32 v135, v129, 16, 1
	v_bfe_u32 v136, v132, 16, 1
	v_bfe_u32 v137, v133, 16, 1
	v_add3_u32 v133, v133, v137, s76
	v_add3_u32 v132, v132, v136, s76
	v_add3_u32 v129, v129, v135, s76
	v_add3_u32 v128, v128, v134, s76
	v_lshrrev_b32_e32 v128, 16, v128
	v_lshrrev_b32_e32 v129, 16, v129
	v_lshrrev_b32_e32 v132, 16, v132
	v_lshrrev_b32_e32 v133, 16, v133
	v_and_or_b32 v131, v131, s77, v133
	v_and_or_b32 v130, v130, s77, v132
	v_and_or_b32 v129, v138, s77, v129
	v_and_or_b32 v128, v139, s77, v128
	ds_read_b128 v[132:135], v197 offset:35040
	v_mov_b32_e32 v142, v236
	s_waitcnt lgkmcnt(0)
	v_mfma_f32_32x32x16_bf16 v[48:63], v[128:131], v[132:135], v[48:63]
	ds_read_b128 v[132:135], v197 offset:43744
	s_waitcnt lgkmcnt(0)
	s_barrier
	v_cndmask_b32_e64 v233, -1, 1, s[36:37]
	v_mfma_f32_32x32x16_bf16 v[32:47], v[128:131], v[132:135], v[32:47]
	v_mov_b32_e32 v128, v235
	v_mov_b32_e32 v135, 0
	v_lshlrev_b32_e32 v134, 2, v142
	v_lshl_add_u32 v136, v128, 2, 0
	v_add_u32_e32 v130, v134, v237
	ds_read2st64_b32 v[132:133], v136 offset0:204 offset1:206
	v_mul_i32_i24_e32 v208, v130, v233
	v_mul_i32_i24_e32 v229, v128, v233
	s_nop 0
	v_cmp_le_i32_e32 vcc, v229, v208
	v_lshl_add_u32 v129, v130, 2, 0
	v_mov_b32_e32 v131, 0
	s_and_saveexec_b64 s[0:1], vcc
	s_cbranch_execz .LBB0_998
	ds_read_b32 v131, v129 offset:52224
	s_waitcnt lgkmcnt(0)
	v_sub_f32_e32 v131, v131, v132
	v_mul_f32_e32 v131, 0x3fb8aa3b, v131
	v_exp_f32_e32 v131, v131
	s_nop 0
	v_mul_f32_e32 v112, v112, v131
	v_mul_f32_e32 v131, v133, v112
.LBB0_998:
	s_or_b64 exec, exec, s[0:1]
	v_lshlrev_b32_e32 v143, 1, v128
	v_bfe_u32 v137, v131, 16, 1
	v_sub_u32_e32 v112, v136, v143
	v_add3_u32 v131, v131, v137, s76
	v_mul_lo_u32 v137, v130, s52
	v_add_u32_e32 v138, v112, v137
	ds_write_b16_d16_hi v138, v131
	v_or_b32_e32 v131, 1, v237
	v_add_u32_e32 v131, v134, v131
	v_mul_i32_i24_e32 v209, v131, v233
	v_cmp_le_i32_e32 vcc, v229, v209
	s_and_saveexec_b64 s[0:1], vcc
	s_cbranch_execz .LBB0_1000
	ds_read_b32 v135, v129 offset:52228
	s_waitcnt lgkmcnt(0)
	v_sub_f32_e32 v135, v135, v132
	v_mul_f32_e32 v135, 0x3fb8aa3b, v135
	v_exp_f32_e32 v135, v135
	s_nop 0
	v_mul_f32_e32 v113, v113, v135
	v_mul_f32_e32 v135, v133, v113
.LBB0_1000:
	s_or_b64 exec, exec, s[0:1]
	v_bfe_u32 v113, v135, 16, 1
	v_add3_u32 v113, v135, v113, s76
	v_mul_lo_u32 v135, v131, s52
	v_add_u32_e32 v140, v112, v135
	ds_write_b16_d16_hi v140, v113
	v_or_b32_e32 v113, 2, v237
	v_add_u32_e32 v139, v134, v113
	v_mul_i32_i24_e32 v210, v139, v233
	v_cmp_le_i32_e32 vcc, v229, v210
	v_mov_b32_e32 v113, 0
	v_mov_b32_e32 v135, 0
	s_and_saveexec_b64 s[0:1], vcc
	s_cbranch_execz .LBB0_1002
	ds_read_b32 v135, v129 offset:52232
	s_waitcnt lgkmcnt(0)
	v_sub_f32_e32 v135, v135, v132
	v_mul_f32_e32 v135, 0x3fb8aa3b, v135
	v_exp_f32_e32 v135, v135
	s_nop 0
	v_mul_f32_e32 v114, v114, v135
	v_mul_f32_e32 v135, v133, v114
.LBB0_1002:
	s_or_b64 exec, exec, s[0:1]
	v_bfe_u32 v114, v135, 16, 1
	v_add3_u32 v114, v135, v114, s76
	v_mul_lo_u32 v135, v139, s52
	v_add_u32_e32 v144, v112, v135
	ds_write_b16_d16_hi v144, v114
	v_or_b32_e32 v114, 3, v237
	v_add_u32_e32 v141, v134, v114
	v_mul_i32_i24_e32 v211, v141, v233
	v_cmp_le_i32_e32 vcc, v229, v211
	s_and_saveexec_b64 s[0:1], vcc
	s_cbranch_execz .LBB0_1004
	ds_read_b32 v113, v129 offset:52236
	s_waitcnt lgkmcnt(0)
	v_sub_f32_e32 v113, v113, v132
	v_mul_f32_e32 v113, 0x3fb8aa3b, v113
	v_exp_f32_e32 v113, v113
	s_nop 0
	v_mul_f32_e32 v113, v115, v113
	v_mul_f32_e32 v113, v133, v113
.LBB0_1004:
	s_or_b64 exec, exec, s[0:1]
	v_bfe_u32 v114, v113, 16, 1
	v_add3_u32 v113, v113, v114, s76
	v_mul_lo_u32 v114, v141, s52
	v_add_u32_e32 v146, v112, v114
	ds_write_b16_d16_hi v146, v113
	v_or_b32_e32 v113, 8, v237
	v_add_u32_e32 v145, v134, v113
	v_mul_i32_i24_e32 v212, v145, v233
	v_cmp_le_i32_e32 vcc, v229, v212
	v_mov_b32_e32 v113, 0
	v_mov_b32_e32 v114, 0
	s_and_saveexec_b64 s[0:1], vcc
	s_cbranch_execz .LBB0_1006
	ds_read_b32 v114, v129 offset:52256
	s_waitcnt lgkmcnt(0)
	v_sub_f32_e32 v114, v114, v132
	v_mul_f32_e32 v114, 0x3fb8aa3b, v114
	v_exp_f32_e32 v114, v114
	s_nop 0
	v_mul_f32_e32 v114, v116, v114
	v_mul_f32_e32 v114, v133, v114
.LBB0_1006:
	s_or_b64 exec, exec, s[0:1]
	v_bfe_u32 v115, v114, 16, 1
	v_add3_u32 v114, v114, v115, s76
	v_mul_lo_u32 v115, v145, s52
	v_add_u32_e32 v148, v112, v115
	ds_write_b16_d16_hi v148, v114
	v_or_b32_e32 v114, 9, v237
	v_add_u32_e32 v147, v134, v114
	v_mul_i32_i24_e32 v213, v147, v233
	v_cmp_le_i32_e32 vcc, v229, v213
	s_and_saveexec_b64 s[0:1], vcc
	s_cbranch_execz .LBB0_1008
	ds_read_b32 v113, v129 offset:52260
	s_waitcnt lgkmcnt(0)
	v_sub_f32_e32 v113, v113, v132
	v_mul_f32_e32 v113, 0x3fb8aa3b, v113
	v_exp_f32_e32 v113, v113
	s_nop 0
	v_mul_f32_e32 v113, v117, v113
	v_mul_f32_e32 v113, v133, v113
.LBB0_1008:
	s_or_b64 exec, exec, s[0:1]
	v_bfe_u32 v114, v113, 16, 1
	v_add3_u32 v113, v113, v114, s76
	v_mul_lo_u32 v114, v147, s52
	v_add_u32_e32 v150, v112, v114
	ds_write_b16_d16_hi v150, v113
	v_or_b32_e32 v113, 10, v237
	v_add_u32_e32 v149, v134, v113
	v_mul_i32_i24_e32 v219, v149, v233
	v_cmp_le_i32_e32 vcc, v229, v219
	v_mov_b32_e32 v113, 0
	v_mov_b32_e32 v114, 0
	s_and_saveexec_b64 s[0:1], vcc
	s_cbranch_execz .LBB0_1010
	ds_read_b32 v114, v129 offset:52264
	s_waitcnt lgkmcnt(0)
	v_sub_f32_e32 v114, v114, v132
	v_mul_f32_e32 v114, 0x3fb8aa3b, v114
	v_exp_f32_e32 v114, v114
	s_nop 0
	v_mul_f32_e32 v114, v118, v114
	v_mul_f32_e32 v114, v133, v114
.LBB0_1010:
	s_or_b64 exec, exec, s[0:1]
	v_bfe_u32 v115, v114, 16, 1
	v_add3_u32 v114, v114, v115, s76
	v_mul_lo_u32 v115, v149, s52
	v_add_u32_e32 v152, v112, v115
	ds_write_b16_d16_hi v152, v114
	v_or_b32_e32 v114, 11, v237
	v_add_u32_e32 v151, v134, v114
	v_mul_i32_i24_e32 v220, v151, v233
	v_cmp_le_i32_e32 vcc, v229, v220
	s_and_saveexec_b64 s[0:1], vcc
	s_cbranch_execz .LBB0_1012
	ds_read_b32 v113, v129 offset:52268
	s_waitcnt lgkmcnt(0)
	v_sub_f32_e32 v113, v113, v132
	v_mul_f32_e32 v113, 0x3fb8aa3b, v113
	v_exp_f32_e32 v113, v113
	s_nop 0
	v_mul_f32_e32 v113, v119, v113
	v_mul_f32_e32 v113, v133, v113
.LBB0_1012:
	s_or_b64 exec, exec, s[0:1]
	v_bfe_u32 v114, v113, 16, 1
	v_add3_u32 v113, v113, v114, s76
	v_mul_lo_u32 v114, v151, s52
	v_add_u32_e32 v154, v112, v114
	ds_write_b16_d16_hi v154, v113
	v_or_b32_e32 v113, 16, v237
	v_add_u32_e32 v153, v134, v113
	v_mul_i32_i24_e32 v221, v153, v233
	v_cmp_le_i32_e32 vcc, v229, v221
	v_mov_b32_e32 v113, 0
	v_mov_b32_e32 v114, 0
	s_and_saveexec_b64 s[0:1], vcc
	s_cbranch_execz .LBB0_1014
	ds_read_b32 v114, v129 offset:52288
	s_waitcnt lgkmcnt(0)
	v_sub_f32_e32 v114, v114, v132
	v_mul_f32_e32 v114, 0x3fb8aa3b, v114
	v_exp_f32_e32 v114, v114
	s_nop 0
	v_mul_f32_e32 v114, v120, v114
	v_mul_f32_e32 v114, v133, v114
.LBB0_1014:
	s_or_b64 exec, exec, s[0:1]
	v_bfe_u32 v115, v114, 16, 1
	v_add3_u32 v114, v114, v115, s76
	v_mul_lo_u32 v115, v153, s52
	v_add_u32_e32 v156, v112, v115
	ds_write_b16_d16_hi v156, v114
	v_or_b32_e32 v114, 17, v237
	v_add_u32_e32 v155, v134, v114
	v_mul_i32_i24_e32 v222, v155, v233
	v_cmp_le_i32_e32 vcc, v229, v222
	s_and_saveexec_b64 s[0:1], vcc
	s_cbranch_execz .LBB0_1016
	ds_read_b32 v113, v129 offset:52292
	s_waitcnt lgkmcnt(0)
	v_sub_f32_e32 v113, v113, v132
	v_mul_f32_e32 v113, 0x3fb8aa3b, v113
	v_exp_f32_e32 v113, v113
	s_nop 0
	v_mul_f32_e32 v113, v121, v113
	v_mul_f32_e32 v113, v133, v113
.LBB0_1016:
	s_or_b64 exec, exec, s[0:1]
	v_bfe_u32 v114, v113, 16, 1
	v_add3_u32 v113, v113, v114, s76
	v_mul_lo_u32 v114, v155, s52
	v_add_u32_e32 v175, v134, v165
	v_add_u32_e32 v199, v112, v114
	v_mul_i32_i24_e32 v223, v175, v233
	ds_write_b16_d16_hi v199, v113
	s_nop 0
	v_cmp_le_i32_e32 vcc, v229, v223
	v_mov_b32_e32 v113, 0
	v_mov_b32_e32 v114, 0
	s_and_saveexec_b64 s[0:1], vcc
	s_cbranch_execz .LBB0_1018
	ds_read_b32 v114, v129 offset:52296
	s_waitcnt lgkmcnt(0)
	v_sub_f32_e32 v114, v114, v132
	v_mul_f32_e32 v114, 0x3fb8aa3b, v114
	v_exp_f32_e32 v114, v114
	s_nop 0
	v_mul_f32_e32 v114, v122, v114
	v_mul_f32_e32 v114, v133, v114
.LBB0_1018:
	s_or_b64 exec, exec, s[0:1]
	v_bfe_u32 v115, v114, 16, 1
	v_add3_u32 v114, v114, v115, s76
	v_mul_lo_u32 v115, v175, s52
	v_add_u32_e32 v240, v134, v169
	v_add_u32_e32 v241, v112, v115
	v_mul_i32_i24_e32 v224, v240, v233
	ds_write_b16_d16_hi v241, v114
	s_nop 0
	v_cmp_le_i32_e32 vcc, v229, v224
	s_and_saveexec_b64 s[0:1], vcc
	s_cbranch_execz .LBB0_1020
	ds_read_b32 v113, v129 offset:52300
	s_waitcnt lgkmcnt(0)
	v_sub_f32_e32 v113, v113, v132
	v_mul_f32_e32 v113, 0x3fb8aa3b, v113
	v_exp_f32_e32 v113, v113
	s_nop 0
	v_mul_f32_e32 v113, v123, v113
	v_mul_f32_e32 v113, v133, v113
.LBB0_1020:
	s_or_b64 exec, exec, s[0:1]
	v_bfe_u32 v114, v113, 16, 1
	v_add3_u32 v113, v113, v114, s76
	v_mul_lo_u32 v114, v240, s52
	v_add_u32_e32 v242, v134, v177
	v_add_u32_e32 v243, v112, v114
	v_mul_i32_i24_e32 v225, v242, v233
	ds_write_b16_d16_hi v243, v113
	s_nop 0
	v_cmp_le_i32_e32 vcc, v229, v225
	v_mov_b32_e32 v113, 0
	v_mov_b32_e32 v114, 0
	s_and_saveexec_b64 s[0:1], vcc
	s_cbranch_execz .LBB0_1022
	ds_read_b32 v114, v129 offset:52320
	s_waitcnt lgkmcnt(0)
	v_sub_f32_e32 v114, v114, v132
	v_mul_f32_e32 v114, 0x3fb8aa3b, v114
	v_exp_f32_e32 v114, v114
	s_nop 0
	v_mul_f32_e32 v114, v124, v114
	v_mul_f32_e32 v114, v133, v114
.LBB0_1022:
	s_or_b64 exec, exec, s[0:1]
	v_bfe_u32 v115, v114, 16, 1
	v_add3_u32 v114, v114, v115, s76
	v_mul_lo_u32 v115, v242, s52
	v_add_u32_e32 v244, v134, v181
	v_add_u32_e32 v245, v112, v115
	v_mul_i32_i24_e32 v226, v244, v233
	ds_write_b16_d16_hi v245, v114
	s_nop 0
	v_cmp_le_i32_e32 vcc, v229, v226
	s_and_saveexec_b64 s[0:1], vcc
	s_cbranch_execz .LBB0_1024
	ds_read_b32 v113, v129 offset:52324
	s_waitcnt lgkmcnt(0)
	v_sub_f32_e32 v113, v113, v132
	v_mul_f32_e32 v113, 0x3fb8aa3b, v113
	v_exp_f32_e32 v113, v113
	s_nop 0
	v_mul_f32_e32 v113, v125, v113
	v_mul_f32_e32 v113, v133, v113
.LBB0_1024:
	s_or_b64 exec, exec, s[0:1]
	v_bfe_u32 v114, v113, 16, 1
	v_add3_u32 v113, v113, v114, s76
	v_mul_lo_u32 v114, v244, s52
	v_add_u32_e32 v246, v134, v185
	v_add_u32_e32 v247, v112, v114
	v_mul_i32_i24_e32 v227, v246, v233
	ds_write_b16_d16_hi v247, v113
	s_nop 0
	v_cmp_le_i32_e32 vcc, v229, v227
	v_mov_b32_e32 v113, 0
	v_mov_b32_e32 v114, 0
	s_and_saveexec_b64 s[0:1], vcc
	s_cbranch_execz .LBB0_1026
	ds_read_b32 v114, v129 offset:52328
	s_waitcnt lgkmcnt(0)
	v_sub_f32_e32 v114, v114, v132
	v_mul_f32_e32 v114, 0x3fb8aa3b, v114
	v_exp_f32_e32 v114, v114
	s_nop 0
	v_mul_f32_e32 v114, v126, v114
	v_mul_f32_e32 v114, v133, v114
.LBB0_1026:
	s_or_b64 exec, exec, s[0:1]
	v_bfe_u32 v115, v114, 16, 1
	v_add3_u32 v114, v114, v115, s76
	v_mul_lo_u32 v115, v246, s52
	v_add_u32_e32 v248, v134, v189
	v_add_u32_e32 v249, v112, v115
	v_mul_i32_i24_e32 v228, v248, v233
	ds_write_b16_d16_hi v249, v114
	s_nop 0
	v_cmp_le_i32_e32 vcc, v229, v228
	s_and_saveexec_b64 s[0:1], vcc
	s_cbranch_execz .LBB0_1028
	ds_read_b32 v113, v129 offset:52332
	s_waitcnt lgkmcnt(0)
	v_sub_f32_e32 v113, v113, v132
	v_mul_f32_e32 v113, 0x3fb8aa3b, v113
	v_exp_f32_e32 v113, v113
	s_nop 0
	v_mul_f32_e32 v113, v127, v113
	v_mul_f32_e32 v113, v133, v113
.LBB0_1028:
	s_or_b64 exec, exec, s[0:1]
	v_bfe_u32 v114, v113, 16, 1
	v_add3_u32 v113, v113, v114, s76
	v_mul_lo_u32 v114, v248, s52
	v_add_u32_e32 v250, v112, v114
	ds_write_b16_d16_hi v250, v113
	v_add_u32_e32 v114, 32, v128
	v_add_u32_e32 v251, 0x80, v136
	v_mul_i32_i24_e32 v230, v114, v233
	ds_read2st64_b32 v[112:113], v251 offset0:204 offset1:206
	s_nop 0
	v_cmp_le_i32_e32 vcc, v230, v208
	v_mov_b32_e32 v115, 0
	v_mov_b32_e32 v116, 0
	s_and_saveexec_b64 s[0:1], vcc
	s_cbranch_execz .LBB0_1030
	ds_read_b32 v116, v129 offset:52224
	s_waitcnt lgkmcnt(0)
	v_sub_f32_e32 v116, v116, v112
	v_mul_f32_e32 v116, 0x3fb8aa3b, v116
	v_exp_f32_e32 v116, v116
	s_nop 0
	v_mul_f32_e32 v96, v96, v116
	v_mul_f32_e32 v116, v113, v96
.LBB0_1030:
	s_or_b64 exec, exec, s[0:1]
	v_bfe_u32 v96, v116, 16, 1
	v_add3_u32 v96, v116, v96, s76
	ds_write_b16_d16_hi v138, v96 offset:64
	s_nop 0
	v_cmp_le_i32_e32 vcc, v230, v209
	s_and_saveexec_b64 s[0:1], vcc
	s_cbranch_execz .LBB0_1032
	ds_read_b32 v96, v129 offset:52228
	s_waitcnt lgkmcnt(0)
	v_sub_f32_e32 v96, v96, v112
	v_mul_f32_e32 v96, 0x3fb8aa3b, v96
	v_exp_f32_e32 v96, v96
	s_nop 0
	v_mul_f32_e32 v96, v97, v96
	v_mul_f32_e32 v115, v113, v96
.LBB0_1032:
	s_or_b64 exec, exec, s[0:1]
	v_bfe_u32 v96, v115, 16, 1
	v_add3_u32 v96, v115, v96, s76
	ds_write_b16_d16_hi v140, v96 offset:64
	s_nop 0
	v_cmp_le_i32_e32 vcc, v230, v210
	v_mov_b32_e32 v96, 0
	v_mov_b32_e32 v97, 0
	s_and_saveexec_b64 s[0:1], vcc
	s_cbranch_execz .LBB0_1034
	ds_read_b32 v97, v129 offset:52232
	s_waitcnt lgkmcnt(0)
	v_sub_f32_e32 v97, v97, v112
	v_mul_f32_e32 v97, 0x3fb8aa3b, v97
	v_exp_f32_e32 v97, v97
	s_nop 0
	v_mul_f32_e32 v97, v98, v97
	v_mul_f32_e32 v97, v113, v97
.LBB0_1034:
	s_or_b64 exec, exec, s[0:1]
	v_bfe_u32 v98, v97, 16, 1
	v_add3_u32 v97, v97, v98, s76
	ds_write_b16_d16_hi v144, v97 offset:64
	s_nop 0
	v_cmp_le_i32_e32 vcc, v230, v211
	s_and_saveexec_b64 s[0:1], vcc
	s_cbranch_execz .LBB0_1036
	ds_read_b32 v96, v129 offset:52236
	s_waitcnt lgkmcnt(0)
	v_sub_f32_e32 v96, v96, v112
	v_mul_f32_e32 v96, 0x3fb8aa3b, v96
	v_exp_f32_e32 v96, v96
	s_nop 0
	v_mul_f32_e32 v96, v99, v96
	v_mul_f32_e32 v96, v113, v96
.LBB0_1036:
	s_or_b64 exec, exec, s[0:1]
	v_bfe_u32 v97, v96, 16, 1
	v_add3_u32 v96, v96, v97, s76
	ds_write_b16_d16_hi v146, v96 offset:64
	s_nop 0
	v_cmp_le_i32_e32 vcc, v230, v212
	v_mov_b32_e32 v96, 0
	v_mov_b32_e32 v97, 0
	s_and_saveexec_b64 s[0:1], vcc
	s_cbranch_execz .LBB0_1038
	ds_read_b32 v97, v129 offset:52256
	s_waitcnt lgkmcnt(0)
	v_sub_f32_e32 v97, v97, v112
	v_mul_f32_e32 v97, 0x3fb8aa3b, v97
	v_exp_f32_e32 v97, v97
	s_nop 0
	v_mul_f32_e32 v97, v100, v97
	v_mul_f32_e32 v97, v113, v97
.LBB0_1038:
	s_or_b64 exec, exec, s[0:1]
	v_bfe_u32 v98, v97, 16, 1
	v_add3_u32 v97, v97, v98, s76
	ds_write_b16_d16_hi v148, v97 offset:64
	s_nop 0
	v_cmp_le_i32_e32 vcc, v230, v213
	s_and_saveexec_b64 s[0:1], vcc
	s_cbranch_execz .LBB0_1040
	ds_read_b32 v96, v129 offset:52260
	s_waitcnt lgkmcnt(0)
	v_sub_f32_e32 v96, v96, v112
	v_mul_f32_e32 v96, 0x3fb8aa3b, v96
	v_exp_f32_e32 v96, v96
	s_nop 0
	v_mul_f32_e32 v96, v101, v96
	v_mul_f32_e32 v96, v113, v96
.LBB0_1040:
	s_or_b64 exec, exec, s[0:1]
	v_bfe_u32 v97, v96, 16, 1
	v_add3_u32 v96, v96, v97, s76
	ds_write_b16_d16_hi v150, v96 offset:64
	s_nop 0
	v_cmp_le_i32_e32 vcc, v230, v219
	v_mov_b32_e32 v96, 0
	v_mov_b32_e32 v97, 0
	s_and_saveexec_b64 s[0:1], vcc
	s_cbranch_execz .LBB0_1042
	ds_read_b32 v97, v129 offset:52264
	s_waitcnt lgkmcnt(0)
	v_sub_f32_e32 v97, v97, v112
	v_mul_f32_e32 v97, 0x3fb8aa3b, v97
	v_exp_f32_e32 v97, v97
	s_nop 0
	v_mul_f32_e32 v97, v102, v97
	v_mul_f32_e32 v97, v113, v97
.LBB0_1042:
	s_or_b64 exec, exec, s[0:1]
	v_bfe_u32 v98, v97, 16, 1
	v_add3_u32 v97, v97, v98, s76
	ds_write_b16_d16_hi v152, v97 offset:64
	s_nop 0
	v_cmp_le_i32_e32 vcc, v230, v220
	s_and_saveexec_b64 s[0:1], vcc
	s_cbranch_execz .LBB0_1044
	ds_read_b32 v96, v129 offset:52268
	s_waitcnt lgkmcnt(0)
	v_sub_f32_e32 v96, v96, v112
	v_mul_f32_e32 v96, 0x3fb8aa3b, v96
	v_exp_f32_e32 v96, v96
	s_nop 0
	v_mul_f32_e32 v96, v103, v96
	v_mul_f32_e32 v96, v113, v96
.LBB0_1044:
	s_or_b64 exec, exec, s[0:1]
	v_bfe_u32 v97, v96, 16, 1
	v_add3_u32 v96, v96, v97, s76
	ds_write_b16_d16_hi v154, v96 offset:64
	s_nop 0
	v_cmp_le_i32_e32 vcc, v230, v221
	v_mov_b32_e32 v96, 0
	v_mov_b32_e32 v97, 0
	s_and_saveexec_b64 s[0:1], vcc
	s_cbranch_execz .LBB0_1046
	ds_read_b32 v97, v129 offset:52288
	s_waitcnt lgkmcnt(0)
	v_sub_f32_e32 v97, v97, v112
	v_mul_f32_e32 v97, 0x3fb8aa3b, v97
	v_exp_f32_e32 v97, v97
	s_nop 0
	v_mul_f32_e32 v97, v104, v97
	v_mul_f32_e32 v97, v113, v97
.LBB0_1046:
	s_or_b64 exec, exec, s[0:1]
	v_bfe_u32 v98, v97, 16, 1
	v_add3_u32 v97, v97, v98, s76
	ds_write_b16_d16_hi v156, v97 offset:64
	s_nop 0
	v_cmp_le_i32_e32 vcc, v230, v222
	s_and_saveexec_b64 s[0:1], vcc
	s_cbranch_execz .LBB0_1048
	ds_read_b32 v96, v129 offset:52292
	s_waitcnt lgkmcnt(0)
	v_sub_f32_e32 v96, v96, v112
	v_mul_f32_e32 v96, 0x3fb8aa3b, v96
	v_exp_f32_e32 v96, v96
	s_nop 0
	v_mul_f32_e32 v96, v105, v96
	v_mul_f32_e32 v96, v113, v96
.LBB0_1048:
	s_or_b64 exec, exec, s[0:1]
	v_bfe_u32 v97, v96, 16, 1
	v_add3_u32 v96, v96, v97, s76
	ds_write_b16_d16_hi v199, v96 offset:64
	s_nop 0
	v_cmp_le_i32_e32 vcc, v230, v223
	v_mov_b32_e32 v96, 0
	v_mov_b32_e32 v97, 0
	s_and_saveexec_b64 s[0:1], vcc
	s_cbranch_execz .LBB0_1050
	ds_read_b32 v97, v129 offset:52296
	s_waitcnt lgkmcnt(0)
	v_sub_f32_e32 v97, v97, v112
	v_mul_f32_e32 v97, 0x3fb8aa3b, v97
	v_exp_f32_e32 v97, v97
	s_nop 0
	v_mul_f32_e32 v97, v106, v97
	v_mul_f32_e32 v97, v113, v97
.LBB0_1050:
	s_or_b64 exec, exec, s[0:1]
	v_bfe_u32 v98, v97, 16, 1
	v_add3_u32 v97, v97, v98, s76
	ds_write_b16_d16_hi v241, v97 offset:64
	s_nop 0
	v_cmp_le_i32_e32 vcc, v230, v224
	s_and_saveexec_b64 s[0:1], vcc
	s_cbranch_execz .LBB0_1052
	ds_read_b32 v96, v129 offset:52300
	s_waitcnt lgkmcnt(0)
	v_sub_f32_e32 v96, v96, v112
	v_mul_f32_e32 v96, 0x3fb8aa3b, v96
	v_exp_f32_e32 v96, v96
	s_nop 0
	v_mul_f32_e32 v96, v107, v96
	v_mul_f32_e32 v96, v113, v96
.LBB0_1052:
	s_or_b64 exec, exec, s[0:1]
	v_bfe_u32 v97, v96, 16, 1
	v_add3_u32 v96, v96, v97, s76
	ds_write_b16_d16_hi v243, v96 offset:64
	s_nop 0
	v_cmp_le_i32_e32 vcc, v230, v225
	v_mov_b32_e32 v96, 0
	v_mov_b32_e32 v97, 0
	s_and_saveexec_b64 s[0:1], vcc
	s_cbranch_execz .LBB0_1054
	ds_read_b32 v97, v129 offset:52320
	s_waitcnt lgkmcnt(0)
	v_sub_f32_e32 v97, v97, v112
	v_mul_f32_e32 v97, 0x3fb8aa3b, v97
	v_exp_f32_e32 v97, v97
	s_nop 0
	v_mul_f32_e32 v97, v108, v97
	v_mul_f32_e32 v97, v113, v97
.LBB0_1054:
	s_or_b64 exec, exec, s[0:1]
	v_bfe_u32 v98, v97, 16, 1
	v_add3_u32 v97, v97, v98, s76
	ds_write_b16_d16_hi v245, v97 offset:64
	s_nop 0
	v_cmp_le_i32_e32 vcc, v230, v226
	s_and_saveexec_b64 s[0:1], vcc
	s_cbranch_execz .LBB0_1056
	ds_read_b32 v96, v129 offset:52324
	s_waitcnt lgkmcnt(0)
	v_sub_f32_e32 v96, v96, v112
	v_mul_f32_e32 v96, 0x3fb8aa3b, v96
	v_exp_f32_e32 v96, v96
	s_nop 0
	v_mul_f32_e32 v96, v109, v96
	v_mul_f32_e32 v96, v113, v96
.LBB0_1056:
	s_or_b64 exec, exec, s[0:1]
	v_bfe_u32 v97, v96, 16, 1
	v_add3_u32 v96, v96, v97, s76
	ds_write_b16_d16_hi v247, v96 offset:64
	s_nop 0
	v_cmp_le_i32_e32 vcc, v230, v227
	v_mov_b32_e32 v96, 0
	v_mov_b32_e32 v97, 0
	s_and_saveexec_b64 s[0:1], vcc
	s_cbranch_execz .LBB0_1058
	ds_read_b32 v97, v129 offset:52328
	s_waitcnt lgkmcnt(0)
	v_sub_f32_e32 v97, v97, v112
	v_mul_f32_e32 v97, 0x3fb8aa3b, v97
	v_exp_f32_e32 v97, v97
	s_nop 0
	v_mul_f32_e32 v97, v110, v97
	v_mul_f32_e32 v97, v113, v97
.LBB0_1058:
	s_or_b64 exec, exec, s[0:1]
	v_bfe_u32 v98, v97, 16, 1
	v_add3_u32 v97, v97, v98, s76
	ds_write_b16_d16_hi v249, v97 offset:64
	s_nop 0
	v_cmp_le_i32_e32 vcc, v230, v228
	s_and_saveexec_b64 s[0:1], vcc
	s_cbranch_execz .LBB0_1060
	ds_read_b32 v96, v129 offset:52332
	s_waitcnt lgkmcnt(0)
	v_sub_f32_e32 v96, v96, v112
	v_mul_f32_e32 v96, 0x3fb8aa3b, v96
	v_exp_f32_e32 v96, v96
	s_nop 0
	v_mul_f32_e32 v96, v111, v96
	v_mul_f32_e32 v96, v113, v96
.LBB0_1060:
	s_or_b64 exec, exec, s[0:1]
	v_add_u32_e32 v97, s84, v128
	v_mov_b64_e32 v[98:99], s[4:5]
	v_mad_i64_i32 v[98:99], s[0:1], v97, s9, v[98:99]
	s_waitcnt lgkmcnt(14)
	v_lshlrev_b32_e32 v132, 3, v142
	v_lshl_add_u64 v[98:99], s[86:87], 1, v[98:99]
	v_ashrrev_i32_e32 v133, 31, v132
	v_bfe_u32 v97, v96, 16, 1
	v_lshl_add_u64 v[134:135], v[132:133], 1, v[98:99]
	v_add3_u32 v96, v96, v97, s76
	ds_write_b16_d16_hi v250, v96 offset:64
	global_load_dwordx4 v[124:127], v[134:135], off
	global_load_dwordx4 v[120:123], v[134:135], off offset:32
	global_load_dwordx4 v[116:119], v[134:135], off offset:64
	global_load_dwordx4 v[112:115], v[134:135], off offset:96
	global_load_dwordx4 v[108:111], v[134:135], off offset:128
	global_load_dwordx4 v[104:107], v[134:135], off offset:160
	global_load_dwordx4 v[100:103], v[134:135], off offset:192
	global_load_dwordx4 v[96:99], v[134:135], off offset:224
	v_add_u32_e32 v252, 64, v128
	v_mul_i32_i24_e32 v231, v252, v233
	ds_read2st64_b32 v[136:137], v136 offset0:205 offset1:207
	v_mov_b32_e32 v214, 0
	v_cmp_le_i32_e32 vcc, v231, v208
	v_mov_b32_e32 v206, 0
	s_and_saveexec_b64 s[0:1], vcc
	s_cbranch_execz .LBB0_1062
	ds_read_b32 v206, v129 offset:52224
	s_waitcnt lgkmcnt(0)
	v_sub_f32_e32 v206, v206, v136
	v_mul_f32_e32 v206, 0x3fb8aa3b, v206
	v_exp_f32_e32 v206, v206
	s_nop 0
	v_mul_f32_e32 v80, v80, v206
	v_mul_f32_e32 v206, v137, v80
.LBB0_1062:
	s_or_b64 exec, exec, s[0:1]
	v_bfe_u32 v80, v206, 16, 1
	v_add3_u32 v80, v206, v80, s76
	ds_write_b16_d16_hi v138, v80 offset:128
	s_nop 0
	v_cmp_le_i32_e32 vcc, v231, v209
	s_and_saveexec_b64 s[0:1], vcc
	s_cbranch_execz .LBB0_1064
	ds_read_b32 v80, v129 offset:52228
	s_waitcnt lgkmcnt(0)
	v_sub_f32_e32 v80, v80, v136
	v_mul_f32_e32 v80, 0x3fb8aa3b, v80
	v_exp_f32_e32 v80, v80
	s_nop 0
	v_mul_f32_e32 v80, v81, v80
	v_mul_f32_e32 v214, v137, v80
.LBB0_1064:
	s_or_b64 exec, exec, s[0:1]
	v_bfe_u32 v80, v214, 16, 1
	v_add3_u32 v80, v214, v80, s76
	ds_write_b16_d16_hi v140, v80 offset:128
	s_nop 0
	v_cmp_le_i32_e32 vcc, v231, v210
	v_mov_b32_e32 v80, 0
	v_mov_b32_e32 v81, 0
	s_and_saveexec_b64 s[0:1], vcc
	s_cbranch_execz .LBB0_1066
	ds_read_b32 v81, v129 offset:52232
	s_waitcnt lgkmcnt(0)
	v_sub_f32_e32 v81, v81, v136
	v_mul_f32_e32 v81, 0x3fb8aa3b, v81
	v_exp_f32_e32 v81, v81
	s_nop 0
	v_mul_f32_e32 v81, v82, v81
	v_mul_f32_e32 v81, v137, v81
.LBB0_1066:
	s_or_b64 exec, exec, s[0:1]
	v_bfe_u32 v82, v81, 16, 1
	v_add3_u32 v81, v81, v82, s76
	ds_write_b16_d16_hi v144, v81 offset:128
	s_nop 0
	v_cmp_le_i32_e32 vcc, v231, v211
	s_and_saveexec_b64 s[0:1], vcc
	s_cbranch_execz .LBB0_1068
	ds_read_b32 v80, v129 offset:52236
	s_waitcnt lgkmcnt(0)
	v_sub_f32_e32 v80, v80, v136
	v_mul_f32_e32 v80, 0x3fb8aa3b, v80
	v_exp_f32_e32 v80, v80
	s_nop 0
	v_mul_f32_e32 v80, v83, v80
	v_mul_f32_e32 v80, v137, v80
.LBB0_1068:
	s_or_b64 exec, exec, s[0:1]
	v_bfe_u32 v81, v80, 16, 1
	v_add3_u32 v80, v80, v81, s76
	ds_write_b16_d16_hi v146, v80 offset:128
	s_nop 0
	v_cmp_le_i32_e32 vcc, v231, v212
	v_mov_b32_e32 v80, 0
	v_mov_b32_e32 v81, 0
	s_and_saveexec_b64 s[0:1], vcc
	s_cbranch_execz .LBB0_1070
	ds_read_b32 v81, v129 offset:52256
	s_waitcnt lgkmcnt(0)
	v_sub_f32_e32 v81, v81, v136
	v_mul_f32_e32 v81, 0x3fb8aa3b, v81
	v_exp_f32_e32 v81, v81
	s_nop 0
	v_mul_f32_e32 v81, v84, v81
	v_mul_f32_e32 v81, v137, v81
.LBB0_1070:
	s_or_b64 exec, exec, s[0:1]
	v_bfe_u32 v82, v81, 16, 1
	v_add3_u32 v81, v81, v82, s76
	ds_write_b16_d16_hi v148, v81 offset:128
	s_nop 0
	v_cmp_le_i32_e32 vcc, v231, v213
	s_and_saveexec_b64 s[0:1], vcc
	s_cbranch_execz .LBB0_1072
	ds_read_b32 v80, v129 offset:52260
	s_waitcnt lgkmcnt(0)
	v_sub_f32_e32 v80, v80, v136
	v_mul_f32_e32 v80, 0x3fb8aa3b, v80
	v_exp_f32_e32 v80, v80
	s_nop 0
	v_mul_f32_e32 v80, v85, v80
	v_mul_f32_e32 v80, v137, v80
.LBB0_1072:
	s_or_b64 exec, exec, s[0:1]
	v_bfe_u32 v81, v80, 16, 1
	v_add3_u32 v80, v80, v81, s76
	ds_write_b16_d16_hi v150, v80 offset:128
	s_nop 0
	v_cmp_le_i32_e32 vcc, v231, v219
	v_mov_b32_e32 v80, 0
	v_mov_b32_e32 v81, 0
	s_and_saveexec_b64 s[0:1], vcc
	s_cbranch_execz .LBB0_1074
	ds_read_b32 v81, v129 offset:52264
	s_waitcnt lgkmcnt(0)
	v_sub_f32_e32 v81, v81, v136
	v_mul_f32_e32 v81, 0x3fb8aa3b, v81
	v_exp_f32_e32 v81, v81
	s_nop 0
	v_mul_f32_e32 v81, v86, v81
	v_mul_f32_e32 v81, v137, v81
.LBB0_1074:
	s_or_b64 exec, exec, s[0:1]
	v_bfe_u32 v82, v81, 16, 1
	v_add3_u32 v81, v81, v82, s76
	ds_write_b16_d16_hi v152, v81 offset:128
	s_nop 0
	v_cmp_le_i32_e32 vcc, v231, v220
	s_and_saveexec_b64 s[0:1], vcc
	s_cbranch_execz .LBB0_1076
	ds_read_b32 v80, v129 offset:52268
	s_waitcnt lgkmcnt(0)
	v_sub_f32_e32 v80, v80, v136
	v_mul_f32_e32 v80, 0x3fb8aa3b, v80
	v_exp_f32_e32 v80, v80
	s_nop 0
	v_mul_f32_e32 v80, v87, v80
	v_mul_f32_e32 v80, v137, v80
.LBB0_1076:
	s_or_b64 exec, exec, s[0:1]
	v_bfe_u32 v81, v80, 16, 1
	v_add3_u32 v80, v80, v81, s76
	ds_write_b16_d16_hi v154, v80 offset:128
	s_nop 0
	v_cmp_le_i32_e32 vcc, v231, v221
	v_mov_b32_e32 v80, 0
	v_mov_b32_e32 v81, 0
	s_and_saveexec_b64 s[0:1], vcc
	s_cbranch_execz .LBB0_1078
	ds_read_b32 v81, v129 offset:52288
	s_waitcnt lgkmcnt(0)
	v_sub_f32_e32 v81, v81, v136
	v_mul_f32_e32 v81, 0x3fb8aa3b, v81
	v_exp_f32_e32 v81, v81
	s_nop 0
	v_mul_f32_e32 v81, v88, v81
	v_mul_f32_e32 v81, v137, v81
.LBB0_1078:
	s_or_b64 exec, exec, s[0:1]
	v_bfe_u32 v82, v81, 16, 1
	v_add3_u32 v81, v81, v82, s76
	ds_write_b16_d16_hi v156, v81 offset:128
	s_nop 0
	v_cmp_le_i32_e32 vcc, v231, v222
	s_and_saveexec_b64 s[0:1], vcc
	s_cbranch_execz .LBB0_1080
	ds_read_b32 v80, v129 offset:52292
	s_waitcnt lgkmcnt(0)
	v_sub_f32_e32 v80, v80, v136
	v_mul_f32_e32 v80, 0x3fb8aa3b, v80
	v_exp_f32_e32 v80, v80
	s_nop 0
	v_mul_f32_e32 v80, v89, v80
	v_mul_f32_e32 v80, v137, v80
.LBB0_1080:
	s_or_b64 exec, exec, s[0:1]
	v_bfe_u32 v81, v80, 16, 1
	v_add3_u32 v80, v80, v81, s76
	ds_write_b16_d16_hi v199, v80 offset:128
	s_nop 0
	v_cmp_le_i32_e32 vcc, v231, v223
	v_mov_b32_e32 v80, 0
	v_mov_b32_e32 v81, 0
	s_and_saveexec_b64 s[0:1], vcc
	s_cbranch_execz .LBB0_1082
	ds_read_b32 v81, v129 offset:52296
	s_waitcnt lgkmcnt(0)
	v_sub_f32_e32 v81, v81, v136
	v_mul_f32_e32 v81, 0x3fb8aa3b, v81
	v_exp_f32_e32 v81, v81
	s_nop 0
	v_mul_f32_e32 v81, v90, v81
	v_mul_f32_e32 v81, v137, v81
.LBB0_1082:
	s_or_b64 exec, exec, s[0:1]
	v_bfe_u32 v82, v81, 16, 1
	v_add3_u32 v81, v81, v82, s76
	ds_write_b16_d16_hi v241, v81 offset:128
	s_nop 0
	v_cmp_le_i32_e32 vcc, v231, v224
	s_and_saveexec_b64 s[0:1], vcc
	s_cbranch_execz .LBB0_1084
	ds_read_b32 v80, v129 offset:52300
	s_waitcnt lgkmcnt(0)
	v_sub_f32_e32 v80, v80, v136
	v_mul_f32_e32 v80, 0x3fb8aa3b, v80
	v_exp_f32_e32 v80, v80
	s_nop 0
	v_mul_f32_e32 v80, v91, v80
	v_mul_f32_e32 v80, v137, v80
.LBB0_1084:
	s_or_b64 exec, exec, s[0:1]
	v_bfe_u32 v81, v80, 16, 1
	v_add3_u32 v80, v80, v81, s76
	ds_write_b16_d16_hi v243, v80 offset:128
	s_nop 0
	v_cmp_le_i32_e32 vcc, v231, v225
	v_mov_b32_e32 v80, 0
	v_mov_b32_e32 v81, 0
	s_and_saveexec_b64 s[0:1], vcc
	s_cbranch_execz .LBB0_1086
	ds_read_b32 v81, v129 offset:52320
	s_waitcnt lgkmcnt(0)
	v_sub_f32_e32 v81, v81, v136
	v_mul_f32_e32 v81, 0x3fb8aa3b, v81
	v_exp_f32_e32 v81, v81
	s_nop 0
	v_mul_f32_e32 v81, v92, v81
	v_mul_f32_e32 v81, v137, v81
.LBB0_1086:
	s_or_b64 exec, exec, s[0:1]
	v_bfe_u32 v82, v81, 16, 1
	v_add3_u32 v81, v81, v82, s76
	ds_write_b16_d16_hi v245, v81 offset:128
	s_nop 0
	v_cmp_le_i32_e32 vcc, v231, v226
	s_and_saveexec_b64 s[0:1], vcc
	s_cbranch_execz .LBB0_1088
	ds_read_b32 v80, v129 offset:52324
	s_waitcnt lgkmcnt(0)
	v_sub_f32_e32 v80, v80, v136
	v_mul_f32_e32 v80, 0x3fb8aa3b, v80
	v_exp_f32_e32 v80, v80
	s_nop 0
	v_mul_f32_e32 v80, v93, v80
	v_mul_f32_e32 v80, v137, v80
.LBB0_1088:
	s_or_b64 exec, exec, s[0:1]
	v_bfe_u32 v81, v80, 16, 1
	v_add3_u32 v80, v80, v81, s76
	ds_write_b16_d16_hi v247, v80 offset:128
	s_nop 0
	v_cmp_le_i32_e32 vcc, v231, v227
	v_mov_b32_e32 v80, 0
	v_mov_b32_e32 v81, 0
	s_and_saveexec_b64 s[0:1], vcc
	s_cbranch_execz .LBB0_1090
	ds_read_b32 v81, v129 offset:52328
	s_waitcnt lgkmcnt(0)
	v_sub_f32_e32 v81, v81, v136
	v_mul_f32_e32 v81, 0x3fb8aa3b, v81
	v_exp_f32_e32 v81, v81
	s_nop 0
	v_mul_f32_e32 v81, v94, v81
	v_mul_f32_e32 v81, v137, v81
.LBB0_1090:
	s_or_b64 exec, exec, s[0:1]
	v_bfe_u32 v82, v81, 16, 1
	v_add3_u32 v81, v81, v82, s76
	ds_write_b16_d16_hi v249, v81 offset:128
	s_nop 0
	v_cmp_le_i32_e32 vcc, v231, v228
	s_and_saveexec_b64 s[0:1], vcc
	s_cbranch_execz .LBB0_1092
	ds_read_b32 v80, v129 offset:52332
	s_waitcnt lgkmcnt(0)
	v_sub_f32_e32 v80, v80, v136
	v_mul_f32_e32 v80, 0x3fb8aa3b, v80
	v_exp_f32_e32 v80, v80
	s_nop 0
	v_mul_f32_e32 v80, v95, v80
	v_mul_f32_e32 v80, v137, v80
.LBB0_1092:
	s_or_b64 exec, exec, s[0:1]
	v_bfe_u32 v81, v80, 16, 1
	v_add3_u32 v80, v80, v81, s76
	ds_write_b16_d16_hi v250, v80 offset:128
	v_add_u32_e32 v82, 0x60, v128
	v_mul_i32_i24_e32 v232, v82, v233
	ds_read2st64_b32 v[80:81], v251 offset0:205 offset1:207
	s_nop 0
	v_cmp_le_i32_e32 vcc, v232, v208
	v_mov_b32_e32 v83, 0
	v_mov_b32_e32 v84, 0
	s_and_saveexec_b64 s[0:1], vcc
	s_cbranch_execz .LBB0_1094
	ds_read_b32 v84, v129 offset:52224
	s_waitcnt lgkmcnt(0)
	v_sub_f32_e32 v84, v84, v80
	v_mul_f32_e32 v84, 0x3fb8aa3b, v84
	v_exp_f32_e32 v84, v84
	s_nop 0
	v_mul_f32_e32 v64, v64, v84
	v_mul_f32_e32 v84, v81, v64
.LBB0_1094:
	s_or_b64 exec, exec, s[0:1]
	v_bfe_u32 v64, v84, 16, 1
	v_add3_u32 v64, v84, v64, s76
	ds_write_b16_d16_hi v138, v64 offset:192
	s_nop 0
	v_cmp_le_i32_e32 vcc, v232, v209
	s_and_saveexec_b64 s[0:1], vcc
	s_cbranch_execz .LBB0_1096
	ds_read_b32 v64, v129 offset:52228
	s_waitcnt lgkmcnt(0)
	v_sub_f32_e32 v64, v64, v80
	v_mul_f32_e32 v64, 0x3fb8aa3b, v64
	v_exp_f32_e32 v64, v64
	s_nop 0
	v_mul_f32_e32 v64, v65, v64
	v_mul_f32_e32 v83, v81, v64
.LBB0_1096:
	s_or_b64 exec, exec, s[0:1]
	v_bfe_u32 v64, v83, 16, 1
	v_add3_u32 v64, v83, v64, s76
	ds_write_b16_d16_hi v140, v64 offset:192
	s_nop 0
	v_cmp_le_i32_e32 vcc, v232, v210
	v_mov_b32_e32 v64, 0
	v_mov_b32_e32 v65, 0
	s_and_saveexec_b64 s[0:1], vcc
	s_cbranch_execz .LBB0_1098
	ds_read_b32 v65, v129 offset:52232
	s_waitcnt lgkmcnt(0)
	v_sub_f32_e32 v65, v65, v80
	v_mul_f32_e32 v65, 0x3fb8aa3b, v65
	v_exp_f32_e32 v65, v65
	s_nop 0
	v_mul_f32_e32 v65, v66, v65
	v_mul_f32_e32 v65, v81, v65
.LBB0_1098:
	s_or_b64 exec, exec, s[0:1]
	v_bfe_u32 v66, v65, 16, 1
	v_add3_u32 v65, v65, v66, s76
	ds_write_b16_d16_hi v144, v65 offset:192
	s_nop 0
	v_cmp_le_i32_e32 vcc, v232, v211
	s_and_saveexec_b64 s[0:1], vcc
	s_cbranch_execz .LBB0_1100
	ds_read_b32 v64, v129 offset:52236
	s_waitcnt lgkmcnt(0)
	v_sub_f32_e32 v64, v64, v80
	v_mul_f32_e32 v64, 0x3fb8aa3b, v64
	v_exp_f32_e32 v64, v64
	s_nop 0
	v_mul_f32_e32 v64, v67, v64
	v_mul_f32_e32 v64, v81, v64
.LBB0_1100:
	s_or_b64 exec, exec, s[0:1]
	v_bfe_u32 v65, v64, 16, 1
	v_add3_u32 v64, v64, v65, s76
	ds_write_b16_d16_hi v146, v64 offset:192
	s_nop 0
	v_cmp_le_i32_e32 vcc, v232, v212
	v_mov_b32_e32 v64, 0
	v_mov_b32_e32 v65, 0
	s_and_saveexec_b64 s[0:1], vcc
	s_cbranch_execz .LBB0_1102
	ds_read_b32 v65, v129 offset:52256
	s_waitcnt lgkmcnt(0)
	v_sub_f32_e32 v65, v65, v80
	v_mul_f32_e32 v65, 0x3fb8aa3b, v65
	v_exp_f32_e32 v65, v65
	s_nop 0
	v_mul_f32_e32 v65, v68, v65
	v_mul_f32_e32 v65, v81, v65
.LBB0_1102:
	s_or_b64 exec, exec, s[0:1]
	v_bfe_u32 v66, v65, 16, 1
	v_add3_u32 v65, v65, v66, s76
	ds_write_b16_d16_hi v148, v65 offset:192
	s_nop 0
	v_cmp_le_i32_e32 vcc, v232, v213
	s_and_saveexec_b64 s[0:1], vcc
	s_cbranch_execz .LBB0_1104
	ds_read_b32 v64, v129 offset:52260
	s_waitcnt lgkmcnt(0)
	v_sub_f32_e32 v64, v64, v80
	v_mul_f32_e32 v64, 0x3fb8aa3b, v64
	v_exp_f32_e32 v64, v64
	s_nop 0
	v_mul_f32_e32 v64, v69, v64
	v_mul_f32_e32 v64, v81, v64
.LBB0_1104:
	s_or_b64 exec, exec, s[0:1]
	v_bfe_u32 v65, v64, 16, 1
	v_add3_u32 v64, v64, v65, s76
	ds_write_b16_d16_hi v150, v64 offset:192
	s_nop 0
	v_cmp_le_i32_e32 vcc, v232, v219
	v_mov_b32_e32 v64, 0
	v_mov_b32_e32 v65, 0
	s_and_saveexec_b64 s[0:1], vcc
	s_cbranch_execz .LBB0_1106
	ds_read_b32 v65, v129 offset:52264
	s_waitcnt lgkmcnt(0)
	v_sub_f32_e32 v65, v65, v80
	v_mul_f32_e32 v65, 0x3fb8aa3b, v65
	v_exp_f32_e32 v65, v65
	s_nop 0
	v_mul_f32_e32 v65, v70, v65
	v_mul_f32_e32 v65, v81, v65
.LBB0_1106:
	s_or_b64 exec, exec, s[0:1]
	v_bfe_u32 v66, v65, 16, 1
	v_add3_u32 v65, v65, v66, s76
	ds_write_b16_d16_hi v152, v65 offset:192
	s_nop 0
	v_cmp_le_i32_e32 vcc, v232, v220
	s_and_saveexec_b64 s[0:1], vcc
	s_cbranch_execz .LBB0_1108
	ds_read_b32 v64, v129 offset:52268
	s_waitcnt lgkmcnt(0)
	v_sub_f32_e32 v64, v64, v80
	v_mul_f32_e32 v64, 0x3fb8aa3b, v64
	v_exp_f32_e32 v64, v64
	s_nop 0
	v_mul_f32_e32 v64, v71, v64
	v_mul_f32_e32 v64, v81, v64
.LBB0_1108:
	s_or_b64 exec, exec, s[0:1]
	v_bfe_u32 v65, v64, 16, 1
	v_add3_u32 v64, v64, v65, s76
	ds_write_b16_d16_hi v154, v64 offset:192
	s_nop 0
	v_cmp_le_i32_e32 vcc, v232, v221
	v_mov_b32_e32 v64, 0
	v_mov_b32_e32 v65, 0
	s_and_saveexec_b64 s[0:1], vcc
	s_cbranch_execz .LBB0_1110
	ds_read_b32 v65, v129 offset:52288
	s_waitcnt lgkmcnt(0)
	v_sub_f32_e32 v65, v65, v80
	v_mul_f32_e32 v65, 0x3fb8aa3b, v65
	v_exp_f32_e32 v65, v65
	s_nop 0
	v_mul_f32_e32 v65, v72, v65
	v_mul_f32_e32 v65, v81, v65
.LBB0_1110:
	s_or_b64 exec, exec, s[0:1]
	v_bfe_u32 v66, v65, 16, 1
	v_add3_u32 v65, v65, v66, s76
	ds_write_b16_d16_hi v156, v65 offset:192
	s_nop 0
	v_cmp_le_i32_e32 vcc, v232, v222
	s_and_saveexec_b64 s[0:1], vcc
	s_cbranch_execz .LBB0_1112
	ds_read_b32 v64, v129 offset:52292
	s_waitcnt lgkmcnt(0)
	v_sub_f32_e32 v64, v64, v80
	v_mul_f32_e32 v64, 0x3fb8aa3b, v64
	v_exp_f32_e32 v64, v64
	s_nop 0
	v_mul_f32_e32 v64, v73, v64
	v_mul_f32_e32 v64, v81, v64
.LBB0_1112:
	s_or_b64 exec, exec, s[0:1]
	v_bfe_u32 v65, v64, 16, 1
	v_add3_u32 v64, v64, v65, s76
	ds_write_b16_d16_hi v199, v64 offset:192
	s_nop 0
	v_cmp_le_i32_e32 vcc, v232, v223
	v_mov_b32_e32 v64, 0
	v_mov_b32_e32 v65, 0
	s_and_saveexec_b64 s[0:1], vcc
	s_cbranch_execz .LBB0_1114
	ds_read_b32 v65, v129 offset:52296
	s_waitcnt lgkmcnt(0)
	v_sub_f32_e32 v65, v65, v80
	v_mul_f32_e32 v65, 0x3fb8aa3b, v65
	v_exp_f32_e32 v65, v65
	s_nop 0
	v_mul_f32_e32 v65, v74, v65
	v_mul_f32_e32 v65, v81, v65
.LBB0_1114:
	s_or_b64 exec, exec, s[0:1]
	v_bfe_u32 v66, v65, 16, 1
	v_add3_u32 v65, v65, v66, s76
	ds_write_b16_d16_hi v241, v65 offset:192
	s_nop 0
	v_cmp_le_i32_e32 vcc, v232, v224
	s_and_saveexec_b64 s[0:1], vcc
	s_cbranch_execz .LBB0_1116
	ds_read_b32 v64, v129 offset:52300
	s_waitcnt lgkmcnt(0)
	v_sub_f32_e32 v64, v64, v80
	v_mul_f32_e32 v64, 0x3fb8aa3b, v64
	v_exp_f32_e32 v64, v64
	s_nop 0
	v_mul_f32_e32 v64, v75, v64
	v_mul_f32_e32 v64, v81, v64
.LBB0_1116:
	s_or_b64 exec, exec, s[0:1]
	v_bfe_u32 v65, v64, 16, 1
	v_add3_u32 v64, v64, v65, s76
	ds_write_b16_d16_hi v243, v64 offset:192
	s_nop 0
	v_cmp_le_i32_e32 vcc, v232, v225
	v_mov_b32_e32 v64, 0
	v_mov_b32_e32 v65, 0
	s_and_saveexec_b64 s[0:1], vcc
	s_cbranch_execz .LBB0_1118
	ds_read_b32 v65, v129 offset:52320
	s_waitcnt lgkmcnt(0)
	v_sub_f32_e32 v65, v65, v80
	v_mul_f32_e32 v65, 0x3fb8aa3b, v65
	v_exp_f32_e32 v65, v65
	s_nop 0
	v_mul_f32_e32 v65, v76, v65
	v_mul_f32_e32 v65, v81, v65
.LBB0_1118:
	s_or_b64 exec, exec, s[0:1]
	v_bfe_u32 v66, v65, 16, 1
	v_add3_u32 v65, v65, v66, s76
	ds_write_b16_d16_hi v245, v65 offset:192
	s_nop 0
	v_cmp_le_i32_e32 vcc, v232, v226
	s_and_saveexec_b64 s[0:1], vcc
	s_cbranch_execz .LBB0_1120
	ds_read_b32 v64, v129 offset:52324
	s_waitcnt lgkmcnt(0)
	v_sub_f32_e32 v64, v64, v80
	v_mul_f32_e32 v64, 0x3fb8aa3b, v64
	v_exp_f32_e32 v64, v64
	s_nop 0
	v_mul_f32_e32 v64, v77, v64
	v_mul_f32_e32 v64, v81, v64
.LBB0_1120:
	s_or_b64 exec, exec, s[0:1]
	v_bfe_u32 v65, v64, 16, 1
	v_add3_u32 v64, v64, v65, s76
	ds_write_b16_d16_hi v247, v64 offset:192
	s_nop 0
	v_cmp_le_i32_e32 vcc, v232, v227
	v_mov_b32_e32 v64, 0
	v_mov_b32_e32 v65, 0
	s_and_saveexec_b64 s[0:1], vcc
	s_cbranch_execz .LBB0_1122
	ds_read_b32 v65, v129 offset:52328
	s_waitcnt lgkmcnt(0)
	v_sub_f32_e32 v65, v65, v80
	v_mul_f32_e32 v65, 0x3fb8aa3b, v65
	v_exp_f32_e32 v65, v65
	s_nop 0
	v_mul_f32_e32 v65, v78, v65
	v_mul_f32_e32 v65, v81, v65
.LBB0_1122:
	s_or_b64 exec, exec, s[0:1]
	v_bfe_u32 v66, v65, 16, 1
	v_add3_u32 v65, v65, v66, s76
	ds_write_b16_d16_hi v249, v65 offset:192
	s_nop 0
	v_cmp_le_i32_e32 vcc, v232, v228
	s_and_saveexec_b64 s[0:1], vcc
	s_cbranch_execz .LBB0_983
	ds_read_b32 v64, v129 offset:52332
	s_waitcnt lgkmcnt(0)
	v_sub_f32_e32 v64, v64, v80
	v_mul_f32_e32 v64, 0x3fb8aa3b, v64
	v_exp_f32_e32 v64, v64
	s_nop 0
	v_mul_f32_e32 v64, v79, v64
	v_mul_f32_e32 v64, v81, v64
	s_branch .LBB0_983

.LBB0_1139:
	global_load_dwordx4 v[66:69], v[60:61], off offset:-192
	global_load_dwordx4 v[70:73], v[60:61], off offset:-128
	s_mov_b64 s[38:39], 0x100
	s_waitcnt vmcnt(1)
	v_mfma_f32_16x16x32_bf16 v[4:7], v[48:51], v[66:69], v[4:7]
	v_add_u32_e32 v49, s13, v58
	v_add_u32_e32 v48, 0x880, v49
	v_add_u32_e32 v50, 0x870, v49
	v_mfma_f32_16x16x32_bf16 v[0:3], v[52:55], v[66:69], v[0:3]
	v_ashrrev_i32_e32 v49, 31, v48
	v_ashrrev_i32_e32 v51, 31, v50
	v_lshl_add_u64 v[78:79], v[48:49], 1, v[56:57]
	v_lshl_add_u64 v[80:81], v[50:51], 1, v[56:57]
	v_mfma_f32_16x16x32_bf16 v[12:15], v[32:35], v[66:69], v[12:15]
	global_load_dwordx4 v[48:51], v[78:79], off offset:64
	global_load_dwordx4 v[52:55], v[80:81], off offset:64
	s_addk_i32 s13, 0x80
	v_mfma_f32_16x16x32_bf16 v[8:11], v[36:39], v[66:69], v[8:11]
	s_cmpk_lt_u32 s13, 0x780
	global_load_dwordx4 v[74:77], v[60:61], off
	s_waitcnt vmcnt(3)
	v_mfma_f32_16x16x32_bf16 v[4:7], v[32:35], v[70:73], v[4:7]
	global_load_dwordx4 v[32:35], v[78:79], off
	v_mfma_f32_16x16x32_bf16 v[0:3], v[36:39], v[70:73], v[0:3]
	global_load_dwordx4 v[36:39], v[80:81], off
	v_mfma_f32_16x16x32_bf16 v[20:23], v[40:43], v[66:69], v[20:23]
	v_mfma_f32_16x16x32_bf16 v[16:19], v[44:47], v[66:69], v[16:19]
	s_waitcnt vmcnt(1)
	v_mfma_f32_16x16x32_bf16 v[28:31], v[32:35], v[66:69], v[28:31]
	s_waitcnt vmcnt(0)
	v_mfma_f32_16x16x32_bf16 v[24:27], v[36:39], v[66:69], v[24:27]
	global_load_dwordx4 v[66:69], v[60:61], off offset:-64
	v_lshl_add_u64 v[60:61], v[60:61], 0, s[38:39]
	v_mfma_f32_16x16x32_bf16 v[12:15], v[40:43], v[70:73], v[12:15]
	v_mfma_f32_16x16x32_bf16 v[8:11], v[44:47], v[70:73], v[8:11]
	v_mfma_f32_16x16x32_bf16 v[20:23], v[32:35], v[70:73], v[20:23]
	v_mfma_f32_16x16x32_bf16 v[16:19], v[36:39], v[70:73], v[16:19]
	v_mfma_f32_16x16x32_bf16 v[28:31], v[48:51], v[70:73], v[28:31]
	v_mfma_f32_16x16x32_bf16 v[24:27], v[52:55], v[70:73], v[24:27]
	s_waitcnt vmcnt(0)
	v_mfma_f32_16x16x32_bf16 v[4:7], v[40:43], v[66:69], v[4:7]
	global_load_dwordx4 v[40:43], v[78:79], off offset:192
	v_mfma_f32_16x16x32_bf16 v[0:3], v[44:47], v[66:69], v[0:3]
	global_load_dwordx4 v[44:47], v[80:81], off offset:192
	v_mfma_f32_16x16x32_bf16 v[12:15], v[32:35], v[66:69], v[12:15]
	v_mfma_f32_16x16x32_bf16 v[8:11], v[36:39], v[66:69], v[8:11]
	v_mfma_f32_16x16x32_bf16 v[4:7], v[32:35], v[74:77], v[4:7]
	global_load_dwordx4 v[32:35], v[78:79], off offset:128
	v_mfma_f32_16x16x32_bf16 v[0:3], v[36:39], v[74:77], v[0:3]
	global_load_dwordx4 v[36:39], v[80:81], off offset:128
	v_mfma_f32_16x16x32_bf16 v[20:23], v[48:51], v[66:69], v[20:23]
	v_mfma_f32_16x16x32_bf16 v[16:19], v[52:55], v[66:69], v[16:19]
	v_mfma_f32_16x16x32_bf16 v[12:15], v[48:51], v[74:77], v[12:15]
	v_mfma_f32_16x16x32_bf16 v[8:11], v[52:55], v[74:77], v[8:11]
	s_waitcnt vmcnt(1)
	v_mfma_f32_16x16x32_bf16 v[28:31], v[32:35], v[66:69], v[28:31]
	s_waitcnt vmcnt(0)
	v_mfma_f32_16x16x32_bf16 v[24:27], v[36:39], v[66:69], v[24:27]
	v_mfma_f32_16x16x32_bf16 v[20:23], v[32:35], v[74:77], v[20:23]
	v_mfma_f32_16x16x32_bf16 v[16:19], v[36:39], v[74:77], v[16:19]
	v_mfma_f32_16x16x32_bf16 v[28:31], v[40:43], v[74:77], v[28:31]
	v_mfma_f32_16x16x32_bf16 v[24:27], v[44:47], v[74:77], v[24:27]
	s_cbranch_scc1 .LBB0_1139
	v_mov_b64_e32 v[32:33], s[96:97]
	v_mad_i64_i32 v[32:33], s[38:39], v59, s9, v[32:33]
	s_mov_b64 s[38:39], 0x15600200
	s_ashr_i32 s35, s34, 31
	v_lshl_add_u64 v[32:33], v[32:33], 0, s[38:39]
	s_lshl_b64 s[38:39], s[34:35], 2
	s_add_u32 s38, s43, s38
	s_addc_u32 s39, s44, s39
	global_load_dword v38, v173, s[38:39]
	global_load_dword v39, v173, s[38:39] offset:1024
	global_load_dword v40, v173, s[38:39] offset:2048
	global_load_dword v41, v173, s[38:39] offset:3072
	v_mov_b32_e32 v92, 0x1000
	global_load_dword v42, v92, s[38:39]
	global_load_dword v43, v92, s[38:39] offset:1024
	global_load_dword v44, v92, s[38:39] offset:2048
	global_load_dword v45, v92, s[38:39] offset:3072
	v_mov_b32_e32 v92, 0x2000
	global_load_dword v46, v92, s[38:39]
	global_load_dword v47, v92, s[38:39] offset:1024
	global_load_dword v48, v92, s[38:39] offset:2048
	global_load_dword v49, v92, s[38:39] offset:3072
	v_mov_b32_e32 v92, 0x3000
	global_load_dword v50, v92, s[38:39]
	global_load_dword v51, v92, s[38:39] offset:1024
	global_load_dword v52, v92, s[38:39] offset:2048
	global_load_dword v53, v92, s[38:39] offset:3072
	v_mov_b32_e32 v92, 0x4000
	global_load_dword v54, v92, s[38:39]
	global_load_dword v55, v92, s[38:39] offset:1024
	global_load_dword v56, v92, s[38:39] offset:2048
	global_load_dword v57, v92, s[38:39] offset:3072
	v_mov_b32_e32 v92, 0x5000
	global_load_dword v58, v92, s[38:39]
	global_load_dword v65, v92, s[38:39] offset:1024
	global_load_dword v66, v92, s[38:39] offset:2048
	global_load_dword v67, v92, s[38:39] offset:3072
	v_mov_b32_e32 v92, 0x6000
	global_load_dword v68, v92, s[38:39]
	global_load_dword v69, v92, s[38:39] offset:1024
	global_load_dword v70, v92, s[38:39] offset:2048
	global_load_dword v71, v92, s[38:39] offset:3072
	v_mov_b32_e32 v92, 0x7000
	global_load_dword v72, v92, s[38:39]
	global_load_dword v73, v92, s[38:39] offset:1024
	global_load_dword v74, v92, s[38:39] offset:2048
	global_load_dword v75, v92, s[38:39] offset:3072
	v_readlane_b32 s16, v254, 29
	s_lshl_b64 s[36:37], s[36:37], 2
	v_readlane_b32 s18, v254, 31
	v_readlane_b32 s19, v254, 32
	s_add_u32 s36, s18, s36
	s_addc_u32 s37, s19, s37
	global_load_dword v37, v173, s[36:37]
	s_movk_i32 s13, 0x900
	v_lshl_or_b32 v34, v64, 2, v63
	v_mov_b32_e32 v35, 0x100
	v_mad_u32_u24 v172, v62, s13, v35
	v_mov_b32_e32 v35, 0
	v_lshl_add_u64 v[94:95], v[34:35], 1, v[32:33]
	global_load_dwordx2 v[76:77], v[94:95], off
	global_load_dwordx2 v[78:79], v[94:95], off offset:32
	global_load_dwordx2 v[80:81], v[94:95], off offset:64
	global_load_dwordx2 v[82:83], v[94:95], off offset:96
	global_load_dwordx2 v[84:85], v[94:95], off offset:128
	global_load_dwordx2 v[86:87], v[94:95], off offset:160
	global_load_dwordx2 v[88:89], v[94:95], off offset:192
	global_load_dwordx2 v[90:91], v[94:95], off offset:224
	v_readlane_b32 s17, v254, 30
	s_lshl_b64 s[34:35], s[34:35], 1
	v_readlane_b32 s16, v255, 42
	v_readlane_b32 s17, v255, 43
	v_readlane_b32 s20, v254, 33
	v_readlane_b32 s21, v254, 34
	v_readlane_b32 s24, v254, 37
	v_readlane_b32 s18, v254, 10
	s_mov_b64 s[20:21], s[46:47]
	s_mov_b32 s24, s64
	v_readlane_b32 s22, v254, 35
	v_readlane_b32 s23, v254, 36
	v_readlane_b32 s25, v254, 38
	v_readlane_b32 s26, v254, 39
	v_readlane_b32 s27, v254, 40
	v_readlane_b32 s28, v254, 41
	v_readlane_b32 s29, v254, 42
	v_readlane_b32 s30, v254, 43
	v_readlane_b32 s31, v254, 44
	v_readlane_b32 s19, v254, 11
	s_add_u32 s38, s16, s34
	s_addc_u32 s39, s17, s35
	s_add_u32 s36, s6, s34
	s_addc_u32 s37, s7, s35
	v_lshlrev_b32_e32 v142, 13, v62
	v_lshl_add_u32 v142, v34, 2, v142
	s_waitcnt vmcnt(0)
	v_add_f32_e32 v36, 0, v38
	v_add_f32_e32 v36, v36, v39
	v_add_f32_e32 v36, v36, v40
	v_add_f32_e32 v36, v36, v41
	v_add_f32_e32 v36, v36, v42
	v_add_f32_e32 v36, v36, v43
	v_add_f32_e32 v36, v36, v44
	v_add_f32_e32 v36, v36, v45
	v_add_f32_e32 v36, v36, v46
	v_add_f32_e32 v36, v36, v47
	v_add_f32_e32 v36, v36, v48
	v_add_f32_e32 v36, v36, v49
	v_add_f32_e32 v36, v36, v50
	v_add_f32_e32 v36, v36, v51
	v_add_f32_e32 v36, v36, v52
	v_add_f32_e32 v36, v36, v53
	v_add_f32_e32 v36, v36, v54
	v_add_f32_e32 v36, v36, v55
	v_add_f32_e32 v36, v36, v56
	v_add_f32_e32 v36, v36, v57
	v_add_f32_e32 v36, v36, v58
	v_add_f32_e32 v36, v36, v65
	v_add_f32_e32 v36, v36, v66
	v_add_f32_e32 v36, v36, v67
	v_add_f32_e32 v36, v36, v68
	v_add_f32_e32 v36, v36, v69
	v_add_f32_e32 v36, v36, v70
	v_add_f32_e32 v36, v36, v71
	v_add_f32_e32 v36, v36, v72
	v_add_f32_e32 v36, v36, v73
	v_add_f32_e32 v36, v36, v74
	v_add_f32_e32 v36, v36, v75
	s_mov_b32 s13, 0x800000
	v_add_f32_e32 v36, 0x358637bd, v36
	v_cmp_gt_f32_e32 vcc, s13, v36
	v_mul_f32_e32 v35, 0x4b800000, v36
	s_movk_i32 s13, 0x900
	s_nop 0
	v_cndmask_b32_e32 v36, v36, v35, vcc
	v_rsq_f32_e32 v36, v36
	s_nop 0
	v_mul_f32_e32 v35, 0x45800000, v36
	v_cndmask_b32_e32 v36, v36, v35, vcc
	v_lshlrev_b32_e32 v92, 16, v76
	v_mul_f32_e32 v92, v37, v92
	v_fmac_f32_e32 v92, v28, v36
	v_mov_b32_e32 v28, v92
	v_and_b32_e32 v92, 0xffff0000, v76
	v_mul_f32_e32 v92, v37, v92
	v_fmac_f32_e32 v92, v29, v36
	v_mov_b32_e32 v29, v92
	v_lshlrev_b32_e32 v92, 16, v77
	v_mul_f32_e32 v92, v37, v92
	v_fmac_f32_e32 v92, v30, v36
	v_mov_b32_e32 v30, v92
	v_and_b32_e32 v92, 0xffff0000, v77
	v_mul_f32_e32 v92, v37, v92
	v_fmac_f32_e32 v92, v31, v36
	v_mov_b32_e32 v31, v92
	v_lshlrev_b32_e32 v92, 16, v78
	v_mul_f32_e32 v92, v37, v92
	v_fmac_f32_e32 v92, v24, v36
	v_mov_b32_e32 v24, v92
	v_and_b32_e32 v92, 0xffff0000, v78
	v_mul_f32_e32 v92, v37, v92
	v_fmac_f32_e32 v92, v25, v36
	v_mov_b32_e32 v25, v92
	v_lshlrev_b32_e32 v92, 16, v79
	v_mul_f32_e32 v92, v37, v92
	v_fmac_f32_e32 v92, v26, v36
	v_mov_b32_e32 v26, v92
	v_and_b32_e32 v92, 0xffff0000, v79
	v_mul_f32_e32 v92, v37, v92
	v_fmac_f32_e32 v92, v27, v36
	v_mov_b32_e32 v27, v92
	v_lshlrev_b32_e32 v92, 16, v80
	v_mul_f32_e32 v92, v37, v92
	v_fmac_f32_e32 v92, v20, v36
	v_mov_b32_e32 v20, v92
	v_and_b32_e32 v92, 0xffff0000, v80
	v_mul_f32_e32 v92, v37, v92
	v_fmac_f32_e32 v92, v21, v36
	v_mov_b32_e32 v21, v92
	v_lshlrev_b32_e32 v92, 16, v81
	v_mul_f32_e32 v92, v37, v92
	v_fmac_f32_e32 v92, v22, v36
	v_mov_b32_e32 v22, v92
	v_and_b32_e32 v92, 0xffff0000, v81
	v_mul_f32_e32 v92, v37, v92
	v_fmac_f32_e32 v92, v23, v36
	v_mov_b32_e32 v23, v92
	v_lshlrev_b32_e32 v92, 16, v82
	v_mul_f32_e32 v92, v37, v92
	v_fmac_f32_e32 v92, v16, v36
	v_mov_b32_e32 v16, v92
	v_and_b32_e32 v92, 0xffff0000, v82
	v_mul_f32_e32 v92, v37, v92
	v_fmac_f32_e32 v92, v17, v36
	v_mov_b32_e32 v17, v92
	v_lshlrev_b32_e32 v92, 16, v83
	v_mul_f32_e32 v92, v37, v92
	v_fmac_f32_e32 v92, v18, v36
	v_mov_b32_e32 v18, v92
	v_and_b32_e32 v92, 0xffff0000, v83
	v_mul_f32_e32 v92, v37, v92
	v_fmac_f32_e32 v92, v19, v36
	v_mov_b32_e32 v19, v92
	v_lshlrev_b32_e32 v92, 16, v84
	v_mul_f32_e32 v92, v37, v92
	v_fmac_f32_e32 v92, v12, v36
	v_mov_b32_e32 v12, v92
	v_and_b32_e32 v92, 0xffff0000, v84
	v_mul_f32_e32 v92, v37, v92
	v_fmac_f32_e32 v92, v13, v36
	v_mov_b32_e32 v13, v92
	v_lshlrev_b32_e32 v92, 16, v85
	v_mul_f32_e32 v92, v37, v92
	v_fmac_f32_e32 v92, v14, v36
	v_mov_b32_e32 v14, v92
	v_and_b32_e32 v92, 0xffff0000, v85
	v_mul_f32_e32 v92, v37, v92
	v_fmac_f32_e32 v92, v15, v36
	v_mov_b32_e32 v15, v92
	v_lshlrev_b32_e32 v92, 16, v86
	v_mul_f32_e32 v92, v37, v92
	v_fmac_f32_e32 v92, v8, v36
	v_mov_b32_e32 v8, v92
	v_and_b32_e32 v92, 0xffff0000, v86
	v_mul_f32_e32 v92, v37, v92
	v_fmac_f32_e32 v92, v9, v36
	v_mov_b32_e32 v9, v92
	v_lshlrev_b32_e32 v92, 16, v87
	v_mul_f32_e32 v92, v37, v92
	v_fmac_f32_e32 v92, v10, v36
	v_mov_b32_e32 v10, v92
	v_and_b32_e32 v92, 0xffff0000, v87
	v_mul_f32_e32 v92, v37, v92
	v_fmac_f32_e32 v92, v11, v36
	v_mov_b32_e32 v11, v92
	v_lshlrev_b32_e32 v92, 16, v88
	v_mul_f32_e32 v92, v37, v92
	v_fmac_f32_e32 v92, v4, v36
	v_mov_b32_e32 v4, v92
	v_and_b32_e32 v92, 0xffff0000, v88
	v_mul_f32_e32 v92, v37, v92
	v_fmac_f32_e32 v92, v5, v36
	v_mov_b32_e32 v5, v92
	v_lshlrev_b32_e32 v92, 16, v89
	v_mul_f32_e32 v92, v37, v92
	v_fmac_f32_e32 v92, v6, v36
	v_mov_b32_e32 v6, v92
	v_and_b32_e32 v92, 0xffff0000, v89
	v_mul_f32_e32 v92, v37, v92
	v_fmac_f32_e32 v92, v7, v36
	v_mov_b32_e32 v7, v92
	v_lshlrev_b32_e32 v92, 16, v90
	v_mul_f32_e32 v92, v37, v92
	v_fmac_f32_e32 v92, v0, v36
	v_mov_b32_e32 v0, v92
	v_and_b32_e32 v92, 0xffff0000, v90
	v_mul_f32_e32 v92, v37, v92
	v_fmac_f32_e32 v92, v1, v36
	v_mov_b32_e32 v1, v92
	v_lshlrev_b32_e32 v92, 16, v91
	v_mul_f32_e32 v92, v37, v92
	v_fmac_f32_e32 v92, v2, v36
	v_mov_b32_e32 v2, v92
	v_and_b32_e32 v92, 0xffff0000, v91
	v_mul_f32_e32 v92, v37, v92
	v_fmac_f32_e32 v92, v3, v36
	v_mov_b32_e32 v3, v92
	s_lshl_b32 s38, s34, 16
	s_add_u32 s38, s96, s38
	s_addc_u32 s39, s97, 0
	global_store_dwordx4 v142, v[28:31], s[38:39]
	global_store_dwordx4 v142, v[24:27], s[38:39] offset:64
	global_store_dwordx4 v142, v[20:23], s[38:39] offset:128
	global_store_dwordx4 v142, v[16:19], s[38:39] offset:192
	global_store_dwordx4 v142, v[12:15], s[38:39] offset:256
	global_store_dwordx4 v142, v[8:11], s[38:39] offset:320
	global_store_dwordx4 v142, v[4:7], s[38:39] offset:384
	global_store_dwordx4 v142, v[0:3], s[38:39] offset:448

.Lcmb_top:
	s_waitcnt vmcnt(5)
	v_lshlrev_b32_e32 v64, 16, v32
	v_and_b32_e32 v65, 0xffff0000, v32
	v_lshlrev_b32_e32 v66, 16, v33
	v_and_b32_e32 v67, 0xffff0000, v33
	v_lshlrev_b32_e32 v68, 16, v34
	v_and_b32_e32 v69, 0xffff0000, v34
	v_lshlrev_b32_e32 v70, 16, v35
	v_and_b32_e32 v71, 0xffff0000, v35
	v_lshlrev_b32_e32 v80, 16, v36
	v_and_b32_e32 v81, 0xffff0000, v36
	v_lshlrev_b32_e32 v82, 16, v37
	v_and_b32_e32 v83, 0xffff0000, v37
	v_lshlrev_b32_e32 v84, 16, v38
	v_and_b32_e32 v85, 0xffff0000, v38
	v_lshlrev_b32_e32 v86, 16, v39
	v_and_b32_e32 v87, 0xffff0000, v39
	v_add_f32_e32 v64, v64, v80
	v_add_f32_e32 v65, v65, v81
	v_add_f32_e32 v66, v66, v82
	v_add_f32_e32 v67, v67, v83
	v_add_f32_e32 v68, v68, v84
	v_add_f32_e32 v69, v69, v85
	v_add_f32_e32 v70, v70, v86
	v_add_f32_e32 v71, v71, v87
	v_lshlrev_b32_e32 v80, 16, v40
	v_and_b32_e32 v81, 0xffff0000, v40
	v_lshlrev_b32_e32 v82, 16, v41
	v_and_b32_e32 v83, 0xffff0000, v41
	v_lshlrev_b32_e32 v84, 16, v42
	v_and_b32_e32 v85, 0xffff0000, v42
	v_lshlrev_b32_e32 v86, 16, v43
	v_and_b32_e32 v87, 0xffff0000, v43
	v_fmac_f32_e32 v64, v24, v80
	v_fmac_f32_e32 v65, v24, v81
	v_fmac_f32_e32 v66, v24, v82
	v_fmac_f32_e32 v67, v24, v83
	v_fmac_f32_e32 v68, v24, v84
	v_fmac_f32_e32 v69, v24, v85
	v_fmac_f32_e32 v70, v24, v86
	v_fmac_f32_e32 v71, v24, v87
	v_lshlrev_b32_e32 v72, 16, v44
	v_and_b32_e32 v73, 0xffff0000, v44
	v_lshlrev_b32_e32 v74, 16, v45
	v_and_b32_e32 v75, 0xffff0000, v45
	v_lshlrev_b32_e32 v76, 16, v46
	v_and_b32_e32 v77, 0xffff0000, v46
	v_lshlrev_b32_e32 v78, 16, v47
	v_and_b32_e32 v79, 0xffff0000, v47
	v_mul_f32_e32 v80, 0xbfb8aa3b, v72
	v_mul_f32_e32 v81, 0xbfb8aa3b, v73
	v_mul_f32_e32 v82, 0xbfb8aa3b, v74
	v_mul_f32_e32 v83, 0xbfb8aa3b, v75
	v_mul_f32_e32 v84, 0xbfb8aa3b, v76
	v_mul_f32_e32 v85, 0xbfb8aa3b, v77
	v_mul_f32_e32 v86, 0xbfb8aa3b, v78
	v_mul_f32_e32 v87, 0xbfb8aa3b, v79
	v_exp_f32_e32 v80, v80
	v_exp_f32_e32 v81, v81
	v_exp_f32_e32 v82, v82
	v_exp_f32_e32 v83, v83
	v_exp_f32_e32 v84, v84
	v_exp_f32_e32 v85, v85
	v_exp_f32_e32 v86, v86
	v_exp_f32_e32 v87, v87
	v_add_f32_e32 v80, 1.0, v80
	v_add_f32_e32 v81, 1.0, v81
	v_add_f32_e32 v82, 1.0, v82
	v_add_f32_e32 v83, 1.0, v83
	v_add_f32_e32 v84, 1.0, v84
	v_add_f32_e32 v85, 1.0, v85
	v_add_f32_e32 v86, 1.0, v86
	v_add_f32_e32 v87, 1.0, v87
	v_rcp_f32_e32 v80, v80
	v_rcp_f32_e32 v81, v81
	v_rcp_f32_e32 v82, v82
	v_rcp_f32_e32 v83, v83
	v_rcp_f32_e32 v84, v84
	v_rcp_f32_e32 v85, v85
	v_rcp_f32_e32 v86, v86
	v_rcp_f32_e32 v87, v87
	v_mul_f32_e32 v72, v72, v80
	v_mul_f32_e32 v73, v73, v81
	v_mul_f32_e32 v74, v74, v82
	v_mul_f32_e32 v75, v75, v83
	v_mul_f32_e32 v76, v76, v84
	v_mul_f32_e32 v77, v77, v85
	v_mul_f32_e32 v78, v78, v86
	v_mul_f32_e32 v79, v79, v87
	v_mul_f32_e32 v64, v64, v72
	v_mul_f32_e32 v65, v65, v73
	v_mul_f32_e32 v66, v66, v74
	v_mul_f32_e32 v67, v67, v75
	v_mul_f32_e32 v68, v68, v76
	v_mul_f32_e32 v69, v69, v77
	v_mul_f32_e32 v70, v70, v78
	v_mul_f32_e32 v71, v71, v79
	v_mul_f32_e32 v7, v64, v64
	v_fmac_f32_e32 v7, v65, v65
	v_fmac_f32_e32 v7, v66, v66
	v_fmac_f32_e32 v7, v67, v67
	v_fmac_f32_e32 v7, v68, v68
	v_fmac_f32_e32 v7, v69, v69
	v_fmac_f32_e32 v7, v70, v70
	v_fmac_f32_e32 v7, v71, v71
	s_nop 1
	v_add_f32_dpp v7, v7, v7 quad_perm:[1,0,3,2] row_mask:0xf bank_mask:0xf
	s_nop 1
	v_add_f32_dpp v7, v7, v7 quad_perm:[2,3,0,1] row_mask:0xf bank_mask:0xf
	s_nop 1
	v_add_f32_dpp v7, v7, v7 row_half_mirror row_mask:0xf bank_mask:0xf
	s_nop 1
	v_add_f32_dpp v7, v7, v7 row_mirror row_mask:0xf bank_mask:0xf
	s_nop 1
	ds_bpermute_b32 v8, v5, v7
	s_waitcnt lgkmcnt(0)
	v_add_f32_e32 v7, v7, v8
	v_mov_b32_e32 v8, 0x358637bd
	v_fmac_f32_e32 v8, 0x3b800000, v7
	v_rsq_f32_e32 v8, v8
	s_nop 0
	v_mul_f32_e32 v64, v64, v8
	v_mul_f32_e32 v65, v65, v8
	v_mul_f32_e32 v66, v66, v8
	v_mul_f32_e32 v67, v67, v8
	v_mul_f32_e32 v68, v68, v8
	v_mul_f32_e32 v69, v69, v8
	v_mul_f32_e32 v70, v70, v8
	v_mul_f32_e32 v71, v71, v8
	v_mul_f32_e32 v64, v64, v16
	v_mul_f32_e32 v65, v65, v17
	v_mul_f32_e32 v66, v66, v18
	v_mul_f32_e32 v67, v67, v19
	v_mul_f32_e32 v68, v68, v20
	v_mul_f32_e32 v69, v69, v21
	v_mul_f32_e32 v70, v70, v22
	v_mul_f32_e32 v71, v71, v23
	v_cvt_pk_bf16_f32 v88, v64, v65
	v_cvt_pk_bf16_f32 v89, v66, v67
	v_cvt_pk_bf16_f32 v90, v68, v69
	v_cvt_pk_bf16_f32 v91, v70, v71
	s_nop 0
	global_store_dwordx4 v4, v[88:91], s[80:81] offset:512
	s_add_i32 s28, s27, 2
	s_cmp_lt_u32 s28, s26
	s_cselect_b32 s28, s28, 0
	s_cmp_ge_u32 s28, s23
	s_addc_u32 s44, s28, 0
	s_cmp_ge_u32 s44, s25
	s_addc_u32 s44, s44, 0
	s_lshl_b32 s44, s44, 11
	s_add_i32 s44, s44, s19
	s_lshl_b32 s16, s44, 10
	s_lshl_b32 s17, s44, 11
	s_add_u32 s30, s96, s16
	s_addc_u32 s31, s97, 0
	s_add_u32 s48, s30, 0x3600000
	s_addc_u32 s49, s31, 0
	s_add_u32 s30, s30, 0x5a00000
	s_addc_u32 s31, s31, 0
	s_add_u32 s38, s30, 0x2400000
	s_addc_u32 s39, s31, 0
	s_add_u32 s66, s96, s17
	s_addc_u32 s67, s97, 0
	s_add_u32 s66, s66, 0xea00000
	s_addc_u32 s67, s67, 0
	s_add_u32 s80, s6, s17
	s_addc_u32 s81, s7, 0
	global_load_dwordx4 v[32:35], v4, s[30:31]
	global_load_dwordx4 v[36:39], v4, s[38:39]
	global_load_dwordx4 v[40:43], v4, s[66:67]
	global_load_dwordx4 v[44:47], v4, s[48:49]
	s_waitcnt vmcnt(5)
	v_lshlrev_b32_e32 v64, 16, v48
	v_and_b32_e32 v65, 0xffff0000, v48
	v_lshlrev_b32_e32 v66, 16, v49
	v_and_b32_e32 v67, 0xffff0000, v49
	v_lshlrev_b32_e32 v68, 16, v50
	v_and_b32_e32 v69, 0xffff0000, v50
	v_lshlrev_b32_e32 v70, 16, v51
	v_and_b32_e32 v71, 0xffff0000, v51
	v_lshlrev_b32_e32 v80, 16, v52
	v_and_b32_e32 v81, 0xffff0000, v52
	v_lshlrev_b32_e32 v82, 16, v53
	v_and_b32_e32 v83, 0xffff0000, v53
	v_lshlrev_b32_e32 v84, 16, v54
	v_and_b32_e32 v85, 0xffff0000, v54
	v_lshlrev_b32_e32 v86, 16, v55
	v_and_b32_e32 v87, 0xffff0000, v55
	v_add_f32_e32 v64, v64, v80
	v_add_f32_e32 v65, v65, v81
	v_add_f32_e32 v66, v66, v82
	v_add_f32_e32 v67, v67, v83
	v_add_f32_e32 v68, v68, v84
	v_add_f32_e32 v69, v69, v85
	v_add_f32_e32 v70, v70, v86
	v_add_f32_e32 v71, v71, v87
	v_lshlrev_b32_e32 v80, 16, v56
	v_and_b32_e32 v81, 0xffff0000, v56
	v_lshlrev_b32_e32 v82, 16, v57
	v_and_b32_e32 v83, 0xffff0000, v57
	v_lshlrev_b32_e32 v84, 16, v58
	v_and_b32_e32 v85, 0xffff0000, v58
	v_lshlrev_b32_e32 v86, 16, v59
	v_and_b32_e32 v87, 0xffff0000, v59
	v_fmac_f32_e32 v64, v24, v80
	v_fmac_f32_e32 v65, v24, v81
	v_fmac_f32_e32 v66, v24, v82
	v_fmac_f32_e32 v67, v24, v83
	v_fmac_f32_e32 v68, v24, v84
	v_fmac_f32_e32 v69, v24, v85
	v_fmac_f32_e32 v70, v24, v86
	v_fmac_f32_e32 v71, v24, v87
	v_lshlrev_b32_e32 v72, 16, v60
	v_and_b32_e32 v73, 0xffff0000, v60
	v_lshlrev_b32_e32 v74, 16, v61
	v_and_b32_e32 v75, 0xffff0000, v61
	v_lshlrev_b32_e32 v76, 16, v62
	v_and_b32_e32 v77, 0xffff0000, v62
	v_lshlrev_b32_e32 v78, 16, v63
	v_and_b32_e32 v79, 0xffff0000, v63
	v_mul_f32_e32 v80, 0xbfb8aa3b, v72
	v_mul_f32_e32 v81, 0xbfb8aa3b, v73
	v_mul_f32_e32 v82, 0xbfb8aa3b, v74
	v_mul_f32_e32 v83, 0xbfb8aa3b, v75
	v_mul_f32_e32 v84, 0xbfb8aa3b, v76
	v_mul_f32_e32 v85, 0xbfb8aa3b, v77
	v_mul_f32_e32 v86, 0xbfb8aa3b, v78
	v_mul_f32_e32 v87, 0xbfb8aa3b, v79
	v_exp_f32_e32 v80, v80
	v_exp_f32_e32 v81, v81
	v_exp_f32_e32 v82, v82
	v_exp_f32_e32 v83, v83
	v_exp_f32_e32 v84, v84
	v_exp_f32_e32 v85, v85
	v_exp_f32_e32 v86, v86
	v_exp_f32_e32 v87, v87
	v_add_f32_e32 v80, 1.0, v80
	v_add_f32_e32 v81, 1.0, v81
	v_add_f32_e32 v82, 1.0, v82
	v_add_f32_e32 v83, 1.0, v83
	v_add_f32_e32 v84, 1.0, v84
	v_add_f32_e32 v85, 1.0, v85
	v_add_f32_e32 v86, 1.0, v86
	v_add_f32_e32 v87, 1.0, v87
	v_rcp_f32_e32 v80, v80
	v_rcp_f32_e32 v81, v81
	v_rcp_f32_e32 v82, v82
	v_rcp_f32_e32 v83, v83
	v_rcp_f32_e32 v84, v84
	v_rcp_f32_e32 v85, v85
	v_rcp_f32_e32 v86, v86
	v_rcp_f32_e32 v87, v87
	v_mul_f32_e32 v72, v72, v80
	v_mul_f32_e32 v73, v73, v81
	v_mul_f32_e32 v74, v74, v82
	v_mul_f32_e32 v75, v75, v83
	v_mul_f32_e32 v76, v76, v84
	v_mul_f32_e32 v77, v77, v85
	v_mul_f32_e32 v78, v78, v86
	v_mul_f32_e32 v79, v79, v87
	v_mul_f32_e32 v64, v64, v72
	v_mul_f32_e32 v65, v65, v73
	v_mul_f32_e32 v66, v66, v74
	v_mul_f32_e32 v67, v67, v75
	v_mul_f32_e32 v68, v68, v76
	v_mul_f32_e32 v69, v69, v77
	v_mul_f32_e32 v70, v70, v78
	v_mul_f32_e32 v71, v71, v79
	v_mul_f32_e32 v7, v64, v64
	v_fmac_f32_e32 v7, v65, v65
	v_fmac_f32_e32 v7, v66, v66
	v_fmac_f32_e32 v7, v67, v67
	v_fmac_f32_e32 v7, v68, v68
	v_fmac_f32_e32 v7, v69, v69
	v_fmac_f32_e32 v7, v70, v70
	v_fmac_f32_e32 v7, v71, v71
	s_nop 1
	v_add_f32_dpp v7, v7, v7 quad_perm:[1,0,3,2] row_mask:0xf bank_mask:0xf
	s_nop 1
	v_add_f32_dpp v7, v7, v7 quad_perm:[2,3,0,1] row_mask:0xf bank_mask:0xf
	s_nop 1
	v_add_f32_dpp v7, v7, v7 row_half_mirror row_mask:0xf bank_mask:0xf
	s_nop 1
	v_add_f32_dpp v7, v7, v7 row_mirror row_mask:0xf bank_mask:0xf
	s_nop 1
	ds_bpermute_b32 v8, v5, v7
	s_waitcnt lgkmcnt(0)
	v_add_f32_e32 v7, v7, v8
	v_mov_b32_e32 v8, 0x358637bd
	v_fmac_f32_e32 v8, 0x3b800000, v7
	v_rsq_f32_e32 v8, v8
	s_nop 0
	v_mul_f32_e32 v64, v64, v8
	v_mul_f32_e32 v65, v65, v8
	v_mul_f32_e32 v66, v66, v8
	v_mul_f32_e32 v67, v67, v8
	v_mul_f32_e32 v68, v68, v8
	v_mul_f32_e32 v69, v69, v8
	v_mul_f32_e32 v70, v70, v8
	v_mul_f32_e32 v71, v71, v8
	v_mul_f32_e32 v64, v64, v16
	v_mul_f32_e32 v65, v65, v17
	v_mul_f32_e32 v66, v66, v18
	v_mul_f32_e32 v67, v67, v19
	v_mul_f32_e32 v68, v68, v20
	v_mul_f32_e32 v69, v69, v21
	v_mul_f32_e32 v70, v70, v22
	v_mul_f32_e32 v71, v71, v23
	v_cvt_pk_bf16_f32 v88, v64, v65
	v_cvt_pk_bf16_f32 v89, v66, v67
	v_cvt_pk_bf16_f32 v90, v68, v69
	v_cvt_pk_bf16_f32 v91, v70, v71
	s_nop 0
	global_store_dwordx4 v4, v[88:91], s[82:83] offset:512
	s_add_i32 s28, s27, 3
	s_cmp_lt_u32 s28, s26
	s_cselect_b32 s28, s28, 0
	s_cmp_ge_u32 s28, s23
	s_addc_u32 s44, s28, 0
	s_cmp_ge_u32 s44, s25
	s_addc_u32 s44, s44, 0
	s_lshl_b32 s44, s44, 11
	s_add_i32 s44, s44, s19
	s_lshl_b32 s16, s44, 10
	s_lshl_b32 s17, s44, 11
	s_add_u32 s30, s96, s16
	s_addc_u32 s31, s97, 0
	s_add_u32 s48, s30, 0x3600000
	s_addc_u32 s49, s31, 0
	s_add_u32 s30, s30, 0x5a00000
	s_addc_u32 s31, s31, 0
	s_add_u32 s38, s30, 0x2400000
	s_addc_u32 s39, s31, 0
	s_add_u32 s66, s96, s17
	s_addc_u32 s67, s97, 0
	s_add_u32 s66, s66, 0xea00000
	s_addc_u32 s67, s67, 0
	s_add_u32 s82, s6, s17
	s_addc_u32 s83, s7, 0
	global_load_dwordx4 v[48:51], v4, s[30:31]
	global_load_dwordx4 v[52:55], v4, s[38:39]
	global_load_dwordx4 v[56:59], v4, s[66:67]
	global_load_dwordx4 v[60:63], v4, s[48:49]
	s_add_i32 s27, s27, 2
	s_cmp_lt_u32 s27, s26
	s_cbranch_scc1 .Lcmb_top
	s_waitcnt vmcnt(0)
	v_readlane_b32 s19, v253, 0
	v_lshrrev_b32_e32 v4, 2, v218
	v_and_b32_e32 v5, 3, v218
	v_lshlrev_b32_e32 v6, 17, v4
	v_lshl_add_u32 v6, v5, 6, v6
	v_mul_u32_u24_e32 v7, 4352, v5
	v_lshl_add_u32 v7, v4, 2, v7
	v_mul_u32_u24_e32 v8, 272, v4
	v_lshl_add_u32 v8, v5, 6, v8
	v_lshlrev_b32_e32 v9, 9, v4
	v_lshl_add_u32 v9, v5, 5, v9
	v_lshlrev_b32_e32 v10, 11, v4
	v_lshl_add_u32 v10, v5, 5, v10
	s_mov_b32 s38, 0
.Lhyt_top:
	s_lshl_b32 s16, s38, 9
	s_add_i32 s16, s16, s19
	s_and_b32 s22, s16, 3
	s_bfe_u32 s23, s16, 0x50002
	s_lshr_b32 s25, s16, 7
	s_lshl_b32 s17, s22, 23
	s_lshl_b32 s16, s25, 13
	s_add_i32 s17, s17, s16
	s_lshl_b32 s16, s23, 8
	s_add_i32 s17, s17, s16
	s_add_u32 s26, s96, s17
	s_addc_u32 s27, s97, 0
	s_mul_i32 s17, s25, 0x900
	s_lshl_b32 s16, s23, 6
	s_add_i32 s17, s17, s16
	s_addk_i32 s17, 0x100
	s_lshl_b32 s16, s17, 9
	s_lshl_b32 s39, s22, 7
	s_add_i32 s16, s16, s39
	s_add_u32 s28, s96, 0x16800000
	s_addc_u32 s29, s97, 0
	s_add_u32 s28, s28, s16
	s_addc_u32 s29, s29, 0
	s_lshl_b32 s16, s17, 11
	s_add_i32 s16, s16, s39
	s_add_u32 s30, s6, s16
	s_addc_u32 s31, s7, 0
	global_load_dwordx4 v[16:19], v6, s[26:27]
	global_load_dwordx4 v[20:23], v6, s[26:27] offset:16
	global_load_dwordx4 v[24:27], v6, s[26:27] offset:32
	global_load_dwordx4 v[28:31], v6, s[26:27] offset:48
	global_load_dwordx4 v[32:35], v9, s[28:29]
	global_load_dwordx4 v[36:39], v9, s[28:29] offset:16
	s_waitcnt vmcnt(2)
	ds_write_b32 v7, v16
	ds_write_b32 v7, v17 offset:272
	ds_write_b32 v7, v18 offset:544
	ds_write_b32 v7, v19 offset:816
	ds_write_b32 v7, v20 offset:1088
	ds_write_b32 v7, v21 offset:1360
	ds_write_b32 v7, v22 offset:1632
	ds_write_b32 v7, v23 offset:1904
	ds_write_b32 v7, v24 offset:2176
	ds_write_b32 v7, v25 offset:2448
	ds_write_b32 v7, v26 offset:2720
	ds_write_b32 v7, v27 offset:2992
	ds_write_b32 v7, v28 offset:3264
	ds_write_b32 v7, v29 offset:3536
	ds_write_b32 v7, v30 offset:3808
	ds_write_b32 v7, v31 offset:4080
	s_waitcnt lgkmcnt(0)
	s_barrier
	ds_read_b128 v[16:19], v8
	ds_read_b128 v[20:23], v8 offset:16
	ds_read_b128 v[24:27], v8 offset:32
	ds_read_b128 v[28:31], v8 offset:48
	s_waitcnt vmcnt(0) lgkmcnt(0)
	v_lshlrev_b32_e32 v11, 16, v32
	v_mul_f32_e32 v16, v16, v11
	v_and_b32_e32 v11, 0xffff0000, v32
	v_mul_f32_e32 v17, v17, v11
	v_lshlrev_b32_e32 v11, 16, v33
	v_mul_f32_e32 v18, v18, v11
	v_and_b32_e32 v11, 0xffff0000, v33
	v_mul_f32_e32 v19, v19, v11
	v_lshlrev_b32_e32 v11, 16, v34
	v_mul_f32_e32 v20, v20, v11
	v_and_b32_e32 v11, 0xffff0000, v34
	v_mul_f32_e32 v21, v21, v11
	v_lshlrev_b32_e32 v11, 16, v35
	v_mul_f32_e32 v22, v22, v11
	v_and_b32_e32 v11, 0xffff0000, v35
	v_mul_f32_e32 v23, v23, v11
	v_lshlrev_b32_e32 v11, 16, v36
	v_mul_f32_e32 v24, v24, v11
	v_and_b32_e32 v11, 0xffff0000, v36
	v_mul_f32_e32 v25, v25, v11
	v_lshlrev_b32_e32 v11, 16, v37
	v_mul_f32_e32 v26, v26, v11
	v_and_b32_e32 v11, 0xffff0000, v37
	v_mul_f32_e32 v27, v27, v11
	v_lshlrev_b32_e32 v11, 16, v38
	v_mul_f32_e32 v28, v28, v11
	v_and_b32_e32 v11, 0xffff0000, v38
	v_mul_f32_e32 v29, v29, v11
	v_lshlrev_b32_e32 v11, 16, v39
	v_mul_f32_e32 v30, v30, v11
	v_and_b32_e32 v11, 0xffff0000, v39
	v_mul_f32_e32 v31, v31, v11
	v_cvt_pk_bf16_f32 v32, v16, v17
	v_cvt_pk_bf16_f32 v33, v18, v19
	v_cvt_pk_bf16_f32 v34, v20, v21
	v_cvt_pk_bf16_f32 v35, v22, v23
	v_cvt_pk_bf16_f32 v36, v24, v25
	v_cvt_pk_bf16_f32 v37, v26, v27
	v_cvt_pk_bf16_f32 v38, v28, v29
	v_cvt_pk_bf16_f32 v39, v30, v31
	s_nop 0
	global_store_dwordx4 v10, v[32:35], s[30:31]
	global_store_dwordx4 v10, v[36:39], s[30:31] offset:16
	s_barrier
	s_add_i32 s38, s38, 1
	s_cmp_lt_u32 s38, 4
	s_cbranch_scc1 .Lhyt_top
	s_waitcnt vmcnt(0)
